# np_il + the two k-step MFMAs of each accumulator issued back-to-back inside every MMA block (same instructions reordered, bit-identical accumulation order)
# speedup vs baseline: 1.0823x; 1.0145x over previous
.LBB0_140:
	s_add_u32 s2, s22, 0xfff80080
	s_addc_u32 s20, s23, -1
	s_add_i32 s45, 0, 0x10000
	s_cmp_eq_u32 s44, 28
	s_cselect_b32 s25, s15, s20
	s_cselect_b32 s24, s40, s2
	v_add_u32_e32 v144, s45, v148
	s_cselect_b32 s21, s13, s43
	s_cselect_b32 s20, s41, s42
	s_add_u32 s100, s22, 0xfff80000
	s_addc_u32 s101, s23, -1
	s_add_i32 s2, 0, 0x14000
	s_mov_b32 m0, s35
	ds_read_b128 v[140:143], v144
	ds_read_b128 v[152:155], v144 offset:1024
	ds_read_b128 v[156:159], v144 offset:2048
	ds_read_b128 v[160:163], v144 offset:3072
	global_load_lds_dwordx4 v136, s[100:101]
	s_mov_b32 m0, s36
	v_add_u32_e32 v144, s2, v148
	ds_read_b128 v[164:167], v144
	ds_read_b128 v[168:171], v144 offset:1024
	ds_read_b128 v[172:175], v144 offset:2048
	ds_read_b128 v[176:179], v144 offset:3072
	global_load_lds_dwordx4 v138, s[100:101]
	s_add_i32 m0, s29, 0xc000
	ds_read_b128 v[180:183], v151
	ds_read_b128 v[184:187], v151 offset:1024
	ds_read_b128 v[188:191], v151 offset:2048
	ds_read_b128 v[192:195], v151 offset:3072
	global_load_lds_dwordx4 v136, s[22:23]
	s_add_i32 m0, s29, 0xe000
	ds_read_b128 v[206:209], v151 offset:4096
	ds_read_b128 v[210:213], v151 offset:5120
	ds_read_b128 v[214:217], v151 offset:6144
	ds_read_b128 v[218:221], v151 offset:7168
	global_load_lds_dwordx4 v138, s[22:23]
	s_waitcnt vmcnt(8)
	s_waitcnt lgkmcnt(0)
	s_barrier
	s_waitcnt lgkmcnt(0)
	v_mfma_f32_16x16x32_bf16 v[126:129], v[140:143], v[180:183], v[126:129]
	v_mfma_f32_16x16x32_bf16 v[126:129], v[152:155], v[184:187], v[126:129]
	v_mfma_f32_16x16x32_bf16 v[122:125], v[156:159], v[180:183], v[122:125]
	v_mfma_f32_16x16x32_bf16 v[122:125], v[160:163], v[184:187], v[122:125]
	v_mfma_f32_16x16x32_bf16 v[110:113], v[140:143], v[188:191], v[110:113]
	v_mfma_f32_16x16x32_bf16 v[110:113], v[152:155], v[192:195], v[110:113]
	v_mfma_f32_16x16x32_bf16 v[106:109], v[156:159], v[188:191], v[106:109]
	v_mfma_f32_16x16x32_bf16 v[106:109], v[160:163], v[192:195], v[106:109]
	v_mfma_f32_16x16x32_bf16 v[94:97], v[140:143], v[206:209], v[94:97]
	v_mfma_f32_16x16x32_bf16 v[94:97], v[152:155], v[210:213], v[94:97]
	v_mfma_f32_16x16x32_bf16 v[90:93], v[156:159], v[206:209], v[90:93]
	v_mfma_f32_16x16x32_bf16 v[90:93], v[160:163], v[210:213], v[90:93]
	v_mfma_f32_16x16x32_bf16 v[78:81], v[140:143], v[214:217], v[78:81]
	v_mfma_f32_16x16x32_bf16 v[78:81], v[152:155], v[218:221], v[78:81]
	v_mfma_f32_16x16x32_bf16 v[74:77], v[156:159], v[214:217], v[74:77]
	v_mfma_f32_16x16x32_bf16 v[74:77], v[160:163], v[218:221], v[74:77]
	v_mfma_f32_16x16x32_bf16 v[118:121], v[164:167], v[180:183], v[118:121]
	v_mfma_f32_16x16x32_bf16 v[118:121], v[168:171], v[184:187], v[118:121]
	v_mfma_f32_16x16x32_bf16 v[114:117], v[172:175], v[180:183], v[114:117]
	v_mfma_f32_16x16x32_bf16 v[114:117], v[176:179], v[184:187], v[114:117]
	v_mfma_f32_16x16x32_bf16 v[102:105], v[164:167], v[188:191], v[102:105]
	v_mfma_f32_16x16x32_bf16 v[102:105], v[168:171], v[192:195], v[102:105]
	v_mfma_f32_16x16x32_bf16 v[98:101], v[172:175], v[188:191], v[98:101]
	v_mfma_f32_16x16x32_bf16 v[98:101], v[176:179], v[192:195], v[98:101]
	v_mfma_f32_16x16x32_bf16 v[86:89], v[164:167], v[206:209], v[86:89]
	v_mfma_f32_16x16x32_bf16 v[86:89], v[168:171], v[210:213], v[86:89]
	v_mfma_f32_16x16x32_bf16 v[82:85], v[172:175], v[206:209], v[82:85]
	v_mfma_f32_16x16x32_bf16 v[82:85], v[176:179], v[210:213], v[82:85]
	v_mfma_f32_16x16x32_bf16 v[70:73], v[164:167], v[214:217], v[70:73]
	v_mfma_f32_16x16x32_bf16 v[70:73], v[168:171], v[218:221], v[70:73]
	v_mfma_f32_16x16x32_bf16 v[66:69], v[172:175], v[214:217], v[66:69]
	v_mfma_f32_16x16x32_bf16 v[66:69], v[176:179], v[218:221], v[66:69]
	s_barrier
	s_add_u32 s46, s20, 0x80000
	s_addc_u32 s47, s21, 0
	s_add_i32 s45, s45, s28
	s_mov_b32 m0, s45
	ds_read_b128 v[180:183], v151 offset:16384
	ds_read_b128 v[184:187], v151 offset:17408
	global_load_lds_dwordx4 v0, s[20:21]
	s_add_i32 m0, s45, 0x2000
	s_add_i32 s2, s2, s28
	ds_read_b128 v[188:191], v151 offset:18432
	ds_read_b128 v[192:195], v151 offset:19456
	global_load_lds_dwordx4 v130, s[20:21]
	s_mov_b32 m0, s2
	ds_read_b128 v[206:209], v151 offset:20480
	ds_read_b128 v[210:213], v151 offset:21504
	global_load_lds_dwordx4 v0, s[46:47]
	s_add_i32 m0, s2, 0x2000
	ds_read_b128 v[214:217], v151 offset:22528
	ds_read_b128 v[218:221], v151 offset:23552
	global_load_lds_dwordx4 v130, s[46:47]
	s_waitcnt vmcnt(6)
	s_waitcnt lgkmcnt(0)
	s_barrier
	s_waitcnt lgkmcnt(0)
	v_mfma_f32_16x16x32_bf16 v[62:65], v[140:143], v[180:183], v[62:65]
	v_mfma_f32_16x16x32_bf16 v[62:65], v[152:155], v[184:187], v[62:65]
	v_mfma_f32_16x16x32_bf16 v[58:61], v[156:159], v[180:183], v[58:61]
	v_mfma_f32_16x16x32_bf16 v[58:61], v[160:163], v[184:187], v[58:61]
	v_mfma_f32_16x16x32_bf16 v[46:49], v[140:143], v[188:191], v[46:49]
	v_mfma_f32_16x16x32_bf16 v[46:49], v[152:155], v[192:195], v[46:49]
	v_mfma_f32_16x16x32_bf16 v[42:45], v[156:159], v[188:191], v[42:45]
	v_mfma_f32_16x16x32_bf16 v[42:45], v[160:163], v[192:195], v[42:45]
	v_mfma_f32_16x16x32_bf16 v[30:33], v[140:143], v[206:209], v[30:33]
	v_mfma_f32_16x16x32_bf16 v[30:33], v[152:155], v[210:213], v[30:33]
	v_mfma_f32_16x16x32_bf16 v[26:29], v[156:159], v[206:209], v[26:29]
	v_mfma_f32_16x16x32_bf16 v[26:29], v[160:163], v[210:213], v[26:29]
	v_mfma_f32_16x16x32_bf16 v[14:17], v[140:143], v[214:217], v[14:17]
	v_mfma_f32_16x16x32_bf16 v[14:17], v[152:155], v[218:221], v[14:17]
	v_mfma_f32_16x16x32_bf16 v[10:13], v[156:159], v[214:217], v[10:13]
	v_mfma_f32_16x16x32_bf16 v[10:13], v[160:163], v[218:221], v[10:13]
	v_mfma_f32_16x16x32_bf16 v[54:57], v[164:167], v[180:183], v[54:57]
	v_mfma_f32_16x16x32_bf16 v[54:57], v[168:171], v[184:187], v[54:57]
	v_mfma_f32_16x16x32_bf16 v[50:53], v[172:175], v[180:183], v[50:53]
	v_mfma_f32_16x16x32_bf16 v[50:53], v[176:179], v[184:187], v[50:53]
	v_mfma_f32_16x16x32_bf16 v[38:41], v[164:167], v[188:191], v[38:41]
	v_mfma_f32_16x16x32_bf16 v[38:41], v[168:171], v[192:195], v[38:41]
	v_mfma_f32_16x16x32_bf16 v[34:37], v[172:175], v[188:191], v[34:37]
	v_mfma_f32_16x16x32_bf16 v[34:37], v[176:179], v[192:195], v[34:37]
	v_mfma_f32_16x16x32_bf16 v[22:25], v[164:167], v[206:209], v[22:25]
	v_mfma_f32_16x16x32_bf16 v[22:25], v[168:171], v[210:213], v[22:25]
	v_mfma_f32_16x16x32_bf16 v[18:21], v[172:175], v[206:209], v[18:21]
	v_mfma_f32_16x16x32_bf16 v[18:21], v[176:179], v[210:213], v[18:21]
	v_mfma_f32_16x16x32_bf16 v[6:9], v[164:167], v[214:217], v[6:9]
	v_mfma_f32_16x16x32_bf16 v[6:9], v[168:171], v[218:221], v[6:9]
	v_mfma_f32_16x16x32_bf16 v[2:5], v[172:175], v[214:217], v[2:5]
	v_mfma_f32_16x16x32_bf16 v[2:5], v[176:179], v[218:221], v[2:5]
	s_barrier
	s_add_u32 s24, s24, 0x80000
	s_addc_u32 s25, s25, 0
	s_add_u32 s100, s24, 0xfff80000
	s_addc_u32 s101, s25, -1
	s_add_i32 s2, 0, 0x18000
	s_add_i32 s45, 0, 0x1c000
	v_add_u32_e32 v160, s2, v148
	v_add_u32_e32 v176, s45, v148
	s_mov_b32 m0, s29
	ds_read_b128 v[140:143], v160
	ds_read_b128 v[152:155], v160 offset:1024
	ds_read_b128 v[156:159], v160 offset:2048
	ds_read_b128 v[160:163], v160 offset:3072
	global_load_lds_dwordx4 v134, s[100:101]
	s_mov_b32 m0, s30
	ds_read_b128 v[164:167], v176
	ds_read_b128 v[168:171], v176 offset:1024
	ds_read_b128 v[172:175], v176 offset:2048
	ds_read_b128 v[176:179], v176 offset:3072
	global_load_lds_dwordx4 v132, s[100:101]
	s_mov_b32 m0, s31
	ds_read_b128 v[180:183], v151 offset:32768
	ds_read_b128 v[184:187], v151 offset:33792
	ds_read_b128 v[188:191], v151 offset:34816
	ds_read_b128 v[192:195], v151 offset:35840
	global_load_lds_dwordx4 v134, s[24:25]
	s_mov_b32 m0, s33
	ds_read_b128 v[206:209], v151 offset:36864
	ds_read_b128 v[210:213], v151 offset:37888
	ds_read_b128 v[214:217], v151 offset:38912
	ds_read_b128 v[218:221], v151 offset:39936
	global_load_lds_dwordx4 v132, s[24:25]
	s_waitcnt vmcnt(8)
	s_waitcnt lgkmcnt(0)
	s_barrier
	s_waitcnt lgkmcnt(0)
	v_mfma_f32_16x16x32_bf16 v[126:129], v[140:143], v[180:183], v[126:129]
	v_mfma_f32_16x16x32_bf16 v[126:129], v[152:155], v[184:187], v[126:129]
	v_mfma_f32_16x16x32_bf16 v[122:125], v[156:159], v[180:183], v[122:125]
	v_mfma_f32_16x16x32_bf16 v[122:125], v[160:163], v[184:187], v[122:125]
	v_mfma_f32_16x16x32_bf16 v[110:113], v[140:143], v[188:191], v[110:113]
	v_mfma_f32_16x16x32_bf16 v[110:113], v[152:155], v[192:195], v[110:113]
	v_mfma_f32_16x16x32_bf16 v[106:109], v[156:159], v[188:191], v[106:109]
	v_mfma_f32_16x16x32_bf16 v[106:109], v[160:163], v[192:195], v[106:109]
	v_mfma_f32_16x16x32_bf16 v[94:97], v[140:143], v[206:209], v[94:97]
	v_mfma_f32_16x16x32_bf16 v[94:97], v[152:155], v[210:213], v[94:97]
	v_mfma_f32_16x16x32_bf16 v[90:93], v[156:159], v[206:209], v[90:93]
	v_mfma_f32_16x16x32_bf16 v[90:93], v[160:163], v[210:213], v[90:93]
	v_mfma_f32_16x16x32_bf16 v[78:81], v[140:143], v[214:217], v[78:81]
	v_mfma_f32_16x16x32_bf16 v[78:81], v[152:155], v[218:221], v[78:81]
	v_mfma_f32_16x16x32_bf16 v[74:77], v[156:159], v[214:217], v[74:77]
	v_mfma_f32_16x16x32_bf16 v[74:77], v[160:163], v[218:221], v[74:77]
	v_mfma_f32_16x16x32_bf16 v[118:121], v[164:167], v[180:183], v[118:121]
	v_mfma_f32_16x16x32_bf16 v[118:121], v[168:171], v[184:187], v[118:121]
	v_mfma_f32_16x16x32_bf16 v[114:117], v[172:175], v[180:183], v[114:117]
	v_mfma_f32_16x16x32_bf16 v[114:117], v[176:179], v[184:187], v[114:117]
	v_mfma_f32_16x16x32_bf16 v[102:105], v[164:167], v[188:191], v[102:105]
	v_mfma_f32_16x16x32_bf16 v[102:105], v[168:171], v[192:195], v[102:105]
	v_mfma_f32_16x16x32_bf16 v[98:101], v[172:175], v[188:191], v[98:101]
	v_mfma_f32_16x16x32_bf16 v[98:101], v[176:179], v[192:195], v[98:101]
	v_mfma_f32_16x16x32_bf16 v[86:89], v[164:167], v[206:209], v[86:89]
	v_mfma_f32_16x16x32_bf16 v[86:89], v[168:171], v[210:213], v[86:89]
	v_mfma_f32_16x16x32_bf16 v[82:85], v[172:175], v[206:209], v[82:85]
	v_mfma_f32_16x16x32_bf16 v[82:85], v[176:179], v[210:213], v[82:85]
	v_mfma_f32_16x16x32_bf16 v[70:73], v[164:167], v[214:217], v[70:73]
	v_mfma_f32_16x16x32_bf16 v[70:73], v[168:171], v[218:221], v[70:73]
	v_mfma_f32_16x16x32_bf16 v[66:69], v[172:175], v[214:217], v[66:69]
	v_mfma_f32_16x16x32_bf16 v[66:69], v[176:179], v[218:221], v[66:69]
	s_barrier
	s_add_u32 s20, s20, 0x80080
	s_addc_u32 s21, s21, 0
	s_add_u32 s46, s46, 0xfff80080
	s_addc_u32 s47, s47, -1
	s_add_i32 s2, s2, s28
	s_mov_b32 m0, s2
	ds_read_b128 v[180:183], v151 offset:49152
	ds_read_b128 v[184:187], v151 offset:50176
	global_load_lds_dwordx4 v0, s[46:47]
	s_add_i32 m0, s2, 0x2000
	s_add_i32 s2, s45, s28
	ds_read_b128 v[188:191], v151 offset:51200
	ds_read_b128 v[192:195], v151 offset:52224
	global_load_lds_dwordx4 v130, s[46:47]
	s_mov_b32 m0, s2
	ds_read_b128 v[206:209], v151 offset:53248
	ds_read_b128 v[210:213], v151 offset:54272
	global_load_lds_dwordx4 v0, s[20:21]
	s_add_i32 m0, s2, 0x2000
	ds_read_b128 v[214:217], v151 offset:55296
	ds_read_b128 v[218:221], v151 offset:56320
	global_load_lds_dwordx4 v130, s[20:21]
	s_waitcnt vmcnt(6)
	s_waitcnt lgkmcnt(0)
	s_barrier
	s_waitcnt lgkmcnt(0)
	v_mfma_f32_16x16x32_bf16 v[62:65], v[140:143], v[180:183], v[62:65]
	v_mfma_f32_16x16x32_bf16 v[62:65], v[152:155], v[184:187], v[62:65]
	v_mfma_f32_16x16x32_bf16 v[58:61], v[156:159], v[180:183], v[58:61]
	v_mfma_f32_16x16x32_bf16 v[58:61], v[160:163], v[184:187], v[58:61]
	v_mfma_f32_16x16x32_bf16 v[46:49], v[140:143], v[188:191], v[46:49]
	v_mfma_f32_16x16x32_bf16 v[46:49], v[152:155], v[192:195], v[46:49]
	v_mfma_f32_16x16x32_bf16 v[42:45], v[156:159], v[188:191], v[42:45]
	v_mfma_f32_16x16x32_bf16 v[42:45], v[160:163], v[192:195], v[42:45]
	v_mfma_f32_16x16x32_bf16 v[30:33], v[140:143], v[206:209], v[30:33]
	v_mfma_f32_16x16x32_bf16 v[30:33], v[152:155], v[210:213], v[30:33]
	v_mfma_f32_16x16x32_bf16 v[26:29], v[156:159], v[206:209], v[26:29]
	v_mfma_f32_16x16x32_bf16 v[26:29], v[160:163], v[210:213], v[26:29]
	v_mfma_f32_16x16x32_bf16 v[14:17], v[140:143], v[214:217], v[14:17]
	v_mfma_f32_16x16x32_bf16 v[14:17], v[152:155], v[218:221], v[14:17]
	v_mfma_f32_16x16x32_bf16 v[10:13], v[156:159], v[214:217], v[10:13]
	v_mfma_f32_16x16x32_bf16 v[10:13], v[160:163], v[218:221], v[10:13]
	v_mfma_f32_16x16x32_bf16 v[54:57], v[164:167], v[180:183], v[54:57]
	v_mfma_f32_16x16x32_bf16 v[54:57], v[168:171], v[184:187], v[54:57]
	v_mfma_f32_16x16x32_bf16 v[50:53], v[172:175], v[180:183], v[50:53]
	v_mfma_f32_16x16x32_bf16 v[50:53], v[176:179], v[184:187], v[50:53]
	v_mfma_f32_16x16x32_bf16 v[38:41], v[164:167], v[188:191], v[38:41]
	v_mfma_f32_16x16x32_bf16 v[38:41], v[168:171], v[192:195], v[38:41]
	v_mfma_f32_16x16x32_bf16 v[34:37], v[172:175], v[188:191], v[34:37]
	v_mfma_f32_16x16x32_bf16 v[34:37], v[176:179], v[192:195], v[34:37]
	v_mfma_f32_16x16x32_bf16 v[22:25], v[164:167], v[206:209], v[22:25]
	v_mfma_f32_16x16x32_bf16 v[22:25], v[168:171], v[210:213], v[22:25]
	v_mfma_f32_16x16x32_bf16 v[18:21], v[172:175], v[206:209], v[18:21]
	v_mfma_f32_16x16x32_bf16 v[18:21], v[176:179], v[210:213], v[18:21]
	v_mfma_f32_16x16x32_bf16 v[6:9], v[164:167], v[214:217], v[6:9]
	v_mfma_f32_16x16x32_bf16 v[6:9], v[168:171], v[218:221], v[6:9]
	v_mfma_f32_16x16x32_bf16 v[2:5], v[172:175], v[214:217], v[2:5]
	v_mfma_f32_16x16x32_bf16 v[2:5], v[176:179], v[218:221], v[2:5]
	s_barrier
	s_add_i32 s44, s44, 2
	s_add_u32 s22, s22, 0x100
	s_addc_u32 s23, s23, 0
	s_add_u32 s42, s42, 0x100
	s_addc_u32 s43, s43, 0
	s_cmp_gt_u32 s44, 29
	s_cbranch_scc0 .LBB0_140
	s_and_b64 vcc, exec, s[10:11]
	s_cbranch_vccz .LBB0_143
	s_barrier

.LBB0_168:
	s_add_u32 s2, s26, 0xfff80080
	s_addc_u32 s24, s27, -1
	s_add_i32 s50, 0, 0x10000
	s_cmp_eq_u32 s49, 28
	s_cselect_b32 s29, s19, s24
	s_cselect_b32 s28, s44, s2
	v_add_u32_e32 v144, s50, v152
	s_cselect_b32 s25, s17, s47
	s_cselect_b32 s24, s45, s46
	s_add_u32 s100, s26, 0xfff80000
	s_addc_u32 s101, s27, -1
	s_add_i32 s2, 0, 0x14000
	s_mov_b32 m0, s39
	ds_read_b128 v[140:143], v144
	ds_read_b128 v[148:151], v144 offset:1024
	ds_read_b128 v[156:159], v144 offset:2048
	ds_read_b128 v[160:163], v144 offset:3072
	global_load_lds_dwordx4 v136, s[100:101]
	s_mov_b32 m0, s40
	v_add_u32_e32 v144, s2, v152
	ds_read_b128 v[164:167], v144
	ds_read_b128 v[168:171], v144 offset:1024
	ds_read_b128 v[172:175], v144 offset:2048
	ds_read_b128 v[176:179], v144 offset:3072
	global_load_lds_dwordx4 v138, s[100:101]
	s_add_i32 m0, s33, 0xc000
	ds_read_b128 v[180:183], v155
	ds_read_b128 v[184:187], v155 offset:1024
	ds_read_b128 v[188:191], v155 offset:2048
	ds_read_b128 v[192:195], v155 offset:3072
	global_load_lds_dwordx4 v136, s[26:27]
	s_add_i32 m0, s33, 0xe000
	ds_read_b128 v[206:209], v155 offset:4096
	ds_read_b128 v[210:213], v155 offset:5120
	ds_read_b128 v[214:217], v155 offset:6144
	ds_read_b128 v[218:221], v155 offset:7168
	global_load_lds_dwordx4 v138, s[26:27]
	s_waitcnt vmcnt(8)
	s_waitcnt lgkmcnt(0)
	s_barrier
	s_waitcnt lgkmcnt(0)
	v_mfma_f32_16x16x32_bf16 v[122:125], v[140:143], v[180:183], v[122:125]
	v_mfma_f32_16x16x32_bf16 v[122:125], v[148:151], v[184:187], v[122:125]
	v_mfma_f32_16x16x32_bf16 v[114:117], v[156:159], v[180:183], v[114:117]
	v_mfma_f32_16x16x32_bf16 v[114:117], v[160:163], v[184:187], v[114:117]
	v_mfma_f32_16x16x32_bf16 v[106:109], v[140:143], v[188:191], v[106:109]
	v_mfma_f32_16x16x32_bf16 v[106:109], v[148:151], v[192:195], v[106:109]
	v_mfma_f32_16x16x32_bf16 v[98:101], v[156:159], v[188:191], v[98:101]
	v_mfma_f32_16x16x32_bf16 v[98:101], v[160:163], v[192:195], v[98:101]
	v_mfma_f32_16x16x32_bf16 v[90:93], v[140:143], v[206:209], v[90:93]
	v_mfma_f32_16x16x32_bf16 v[90:93], v[148:151], v[210:213], v[90:93]
	v_mfma_f32_16x16x32_bf16 v[82:85], v[156:159], v[206:209], v[82:85]
	v_mfma_f32_16x16x32_bf16 v[82:85], v[160:163], v[210:213], v[82:85]
	v_mfma_f32_16x16x32_bf16 v[74:77], v[140:143], v[214:217], v[74:77]
	v_mfma_f32_16x16x32_bf16 v[74:77], v[148:151], v[218:221], v[74:77]
	v_mfma_f32_16x16x32_bf16 v[66:69], v[156:159], v[214:217], v[66:69]
	v_mfma_f32_16x16x32_bf16 v[66:69], v[160:163], v[218:221], v[66:69]
	v_mfma_f32_16x16x32_bf16 v[126:129], v[164:167], v[180:183], v[126:129]
	v_mfma_f32_16x16x32_bf16 v[126:129], v[168:171], v[184:187], v[126:129]
	v_mfma_f32_16x16x32_bf16 v[118:121], v[172:175], v[180:183], v[118:121]
	v_mfma_f32_16x16x32_bf16 v[118:121], v[176:179], v[184:187], v[118:121]
	v_mfma_f32_16x16x32_bf16 v[110:113], v[164:167], v[188:191], v[110:113]
	v_mfma_f32_16x16x32_bf16 v[110:113], v[168:171], v[192:195], v[110:113]
	v_mfma_f32_16x16x32_bf16 v[102:105], v[172:175], v[188:191], v[102:105]
	v_mfma_f32_16x16x32_bf16 v[102:105], v[176:179], v[192:195], v[102:105]
	v_mfma_f32_16x16x32_bf16 v[94:97], v[164:167], v[206:209], v[94:97]
	v_mfma_f32_16x16x32_bf16 v[94:97], v[168:171], v[210:213], v[94:97]
	v_mfma_f32_16x16x32_bf16 v[86:89], v[172:175], v[206:209], v[86:89]
	v_mfma_f32_16x16x32_bf16 v[86:89], v[176:179], v[210:213], v[86:89]
	v_mfma_f32_16x16x32_bf16 v[78:81], v[164:167], v[214:217], v[78:81]
	v_mfma_f32_16x16x32_bf16 v[78:81], v[168:171], v[218:221], v[78:81]
	v_mfma_f32_16x16x32_bf16 v[70:73], v[172:175], v[214:217], v[70:73]
	v_mfma_f32_16x16x32_bf16 v[70:73], v[176:179], v[218:221], v[70:73]
	s_barrier
	s_add_u32 s52, s24, 0x80000
	s_addc_u32 s53, s25, 0
	s_add_i32 s50, s50, s35
	s_mov_b32 m0, s50
	ds_read_b128 v[180:183], v155 offset:16384
	ds_read_b128 v[184:187], v155 offset:17408
	global_load_lds_dwordx4 v0, s[24:25]
	s_add_i32 m0, s50, 0x2000
	s_add_i32 s2, s2, s35
	ds_read_b128 v[188:191], v155 offset:18432
	ds_read_b128 v[192:195], v155 offset:19456
	global_load_lds_dwordx4 v130, s[24:25]
	s_mov_b32 m0, s2
	ds_read_b128 v[206:209], v155 offset:20480
	ds_read_b128 v[210:213], v155 offset:21504
	global_load_lds_dwordx4 v0, s[52:53]
	s_add_i32 m0, s2, 0x2000
	ds_read_b128 v[214:217], v155 offset:22528
	ds_read_b128 v[218:221], v155 offset:23552
	global_load_lds_dwordx4 v130, s[52:53]
	s_waitcnt vmcnt(6)
	s_waitcnt lgkmcnt(0)
	s_barrier
	s_waitcnt lgkmcnt(0)
	v_mfma_f32_16x16x32_bf16 v[58:61], v[140:143], v[180:183], v[58:61]
	v_mfma_f32_16x16x32_bf16 v[58:61], v[148:151], v[184:187], v[58:61]
	v_mfma_f32_16x16x32_bf16 v[50:53], v[156:159], v[180:183], v[50:53]
	v_mfma_f32_16x16x32_bf16 v[50:53], v[160:163], v[184:187], v[50:53]
	v_mfma_f32_16x16x32_bf16 v[42:45], v[140:143], v[188:191], v[42:45]
	v_mfma_f32_16x16x32_bf16 v[42:45], v[148:151], v[192:195], v[42:45]
	v_mfma_f32_16x16x32_bf16 v[34:37], v[156:159], v[188:191], v[34:37]
	v_mfma_f32_16x16x32_bf16 v[34:37], v[160:163], v[192:195], v[34:37]
	v_mfma_f32_16x16x32_bf16 v[26:29], v[140:143], v[206:209], v[26:29]
	v_mfma_f32_16x16x32_bf16 v[26:29], v[148:151], v[210:213], v[26:29]
	v_mfma_f32_16x16x32_bf16 v[18:21], v[156:159], v[206:209], v[18:21]
	v_mfma_f32_16x16x32_bf16 v[18:21], v[160:163], v[210:213], v[18:21]
	v_mfma_f32_16x16x32_bf16 v[10:13], v[140:143], v[214:217], v[10:13]
	v_mfma_f32_16x16x32_bf16 v[10:13], v[148:151], v[218:221], v[10:13]
	v_mfma_f32_16x16x32_bf16 v[6:9], v[156:159], v[214:217], v[6:9]
	v_mfma_f32_16x16x32_bf16 v[6:9], v[160:163], v[218:221], v[6:9]
	v_mfma_f32_16x16x32_bf16 v[62:65], v[164:167], v[180:183], v[62:65]
	v_mfma_f32_16x16x32_bf16 v[62:65], v[168:171], v[184:187], v[62:65]
	v_mfma_f32_16x16x32_bf16 v[54:57], v[172:175], v[180:183], v[54:57]
	v_mfma_f32_16x16x32_bf16 v[54:57], v[176:179], v[184:187], v[54:57]
	v_mfma_f32_16x16x32_bf16 v[46:49], v[164:167], v[188:191], v[46:49]
	v_mfma_f32_16x16x32_bf16 v[46:49], v[168:171], v[192:195], v[46:49]
	v_mfma_f32_16x16x32_bf16 v[38:41], v[172:175], v[188:191], v[38:41]
	v_mfma_f32_16x16x32_bf16 v[38:41], v[176:179], v[192:195], v[38:41]
	v_mfma_f32_16x16x32_bf16 v[30:33], v[164:167], v[206:209], v[30:33]
	v_mfma_f32_16x16x32_bf16 v[30:33], v[168:171], v[210:213], v[30:33]
	v_mfma_f32_16x16x32_bf16 v[22:25], v[172:175], v[206:209], v[22:25]
	v_mfma_f32_16x16x32_bf16 v[22:25], v[176:179], v[210:213], v[22:25]
	v_mfma_f32_16x16x32_bf16 v[14:17], v[164:167], v[214:217], v[14:17]
	v_mfma_f32_16x16x32_bf16 v[14:17], v[168:171], v[218:221], v[14:17]
	v_mfma_f32_16x16x32_bf16 v[2:5], v[172:175], v[214:217], v[2:5]
	v_mfma_f32_16x16x32_bf16 v[2:5], v[176:179], v[218:221], v[2:5]
	s_barrier
	s_add_u32 s28, s28, 0x80000
	s_addc_u32 s29, s29, 0
	s_add_u32 s100, s28, 0xfff80000
	s_addc_u32 s101, s29, -1
	s_add_i32 s2, 0, 0x18000
	s_add_i32 s50, 0, 0x1c000
	v_add_u32_e32 v160, s2, v152
	v_add_u32_e32 v176, s50, v152
	s_mov_b32 m0, s33
	ds_read_b128 v[140:143], v160
	ds_read_b128 v[148:151], v160 offset:1024
	ds_read_b128 v[156:159], v160 offset:2048
	ds_read_b128 v[160:163], v160 offset:3072
	global_load_lds_dwordx4 v134, s[100:101]
	s_mov_b32 m0, s36
	ds_read_b128 v[164:167], v176
	ds_read_b128 v[168:171], v176 offset:1024
	ds_read_b128 v[172:175], v176 offset:2048
	ds_read_b128 v[176:179], v176 offset:3072
	global_load_lds_dwordx4 v132, s[100:101]
	s_mov_b32 m0, s37
	ds_read_b128 v[180:183], v155 offset:32768
	ds_read_b128 v[184:187], v155 offset:33792
	ds_read_b128 v[188:191], v155 offset:34816
	ds_read_b128 v[192:195], v155 offset:35840
	global_load_lds_dwordx4 v134, s[28:29]
	s_mov_b32 m0, s38
	ds_read_b128 v[206:209], v155 offset:36864
	ds_read_b128 v[210:213], v155 offset:37888
	ds_read_b128 v[214:217], v155 offset:38912
	ds_read_b128 v[218:221], v155 offset:39936
	global_load_lds_dwordx4 v132, s[28:29]
	s_waitcnt vmcnt(8)
	s_waitcnt lgkmcnt(0)
	s_barrier
	s_waitcnt lgkmcnt(0)
	v_mfma_f32_16x16x32_bf16 v[122:125], v[140:143], v[180:183], v[122:125]
	v_mfma_f32_16x16x32_bf16 v[122:125], v[148:151], v[184:187], v[122:125]
	v_mfma_f32_16x16x32_bf16 v[114:117], v[156:159], v[180:183], v[114:117]
	v_mfma_f32_16x16x32_bf16 v[114:117], v[160:163], v[184:187], v[114:117]
	v_mfma_f32_16x16x32_bf16 v[106:109], v[140:143], v[188:191], v[106:109]
	v_mfma_f32_16x16x32_bf16 v[106:109], v[148:151], v[192:195], v[106:109]
	v_mfma_f32_16x16x32_bf16 v[98:101], v[156:159], v[188:191], v[98:101]
	v_mfma_f32_16x16x32_bf16 v[98:101], v[160:163], v[192:195], v[98:101]
	v_mfma_f32_16x16x32_bf16 v[90:93], v[140:143], v[206:209], v[90:93]
	v_mfma_f32_16x16x32_bf16 v[90:93], v[148:151], v[210:213], v[90:93]
	v_mfma_f32_16x16x32_bf16 v[82:85], v[156:159], v[206:209], v[82:85]
	v_mfma_f32_16x16x32_bf16 v[82:85], v[160:163], v[210:213], v[82:85]
	v_mfma_f32_16x16x32_bf16 v[74:77], v[140:143], v[214:217], v[74:77]
	v_mfma_f32_16x16x32_bf16 v[74:77], v[148:151], v[218:221], v[74:77]
	v_mfma_f32_16x16x32_bf16 v[66:69], v[156:159], v[214:217], v[66:69]
	v_mfma_f32_16x16x32_bf16 v[66:69], v[160:163], v[218:221], v[66:69]
	v_mfma_f32_16x16x32_bf16 v[126:129], v[164:167], v[180:183], v[126:129]
	v_mfma_f32_16x16x32_bf16 v[126:129], v[168:171], v[184:187], v[126:129]
	v_mfma_f32_16x16x32_bf16 v[118:121], v[172:175], v[180:183], v[118:121]
	v_mfma_f32_16x16x32_bf16 v[118:121], v[176:179], v[184:187], v[118:121]
	v_mfma_f32_16x16x32_bf16 v[110:113], v[164:167], v[188:191], v[110:113]
	v_mfma_f32_16x16x32_bf16 v[110:113], v[168:171], v[192:195], v[110:113]
	v_mfma_f32_16x16x32_bf16 v[102:105], v[172:175], v[188:191], v[102:105]
	v_mfma_f32_16x16x32_bf16 v[102:105], v[176:179], v[192:195], v[102:105]
	v_mfma_f32_16x16x32_bf16 v[94:97], v[164:167], v[206:209], v[94:97]
	v_mfma_f32_16x16x32_bf16 v[94:97], v[168:171], v[210:213], v[94:97]
	v_mfma_f32_16x16x32_bf16 v[86:89], v[172:175], v[206:209], v[86:89]
	v_mfma_f32_16x16x32_bf16 v[86:89], v[176:179], v[210:213], v[86:89]
	v_mfma_f32_16x16x32_bf16 v[78:81], v[164:167], v[214:217], v[78:81]
	v_mfma_f32_16x16x32_bf16 v[78:81], v[168:171], v[218:221], v[78:81]
	v_mfma_f32_16x16x32_bf16 v[70:73], v[172:175], v[214:217], v[70:73]
	v_mfma_f32_16x16x32_bf16 v[70:73], v[176:179], v[218:221], v[70:73]
	s_barrier
	s_add_u32 s24, s24, 0x80080
	s_addc_u32 s25, s25, 0
	s_add_u32 s52, s52, 0xfff80080
	s_addc_u32 s53, s53, -1
	s_add_i32 s2, s2, s35
	s_mov_b32 m0, s2
	ds_read_b128 v[180:183], v155 offset:49152
	ds_read_b128 v[184:187], v155 offset:50176
	global_load_lds_dwordx4 v0, s[52:53]
	s_add_i32 m0, s2, 0x2000
	s_add_i32 s2, s50, s35
	ds_read_b128 v[188:191], v155 offset:51200
	ds_read_b128 v[192:195], v155 offset:52224
	global_load_lds_dwordx4 v130, s[52:53]
	s_mov_b32 m0, s2
	ds_read_b128 v[206:209], v155 offset:53248
	ds_read_b128 v[210:213], v155 offset:54272
	global_load_lds_dwordx4 v0, s[24:25]
	s_add_i32 m0, s2, 0x2000
	ds_read_b128 v[214:217], v155 offset:55296
	ds_read_b128 v[218:221], v155 offset:56320
	global_load_lds_dwordx4 v130, s[24:25]
	s_waitcnt vmcnt(6)
	s_waitcnt lgkmcnt(0)
	s_barrier
	s_waitcnt lgkmcnt(0)
	v_mfma_f32_16x16x32_bf16 v[58:61], v[140:143], v[180:183], v[58:61]
	v_mfma_f32_16x16x32_bf16 v[58:61], v[148:151], v[184:187], v[58:61]
	v_mfma_f32_16x16x32_bf16 v[50:53], v[156:159], v[180:183], v[50:53]
	v_mfma_f32_16x16x32_bf16 v[50:53], v[160:163], v[184:187], v[50:53]
	v_mfma_f32_16x16x32_bf16 v[42:45], v[140:143], v[188:191], v[42:45]
	v_mfma_f32_16x16x32_bf16 v[42:45], v[148:151], v[192:195], v[42:45]
	v_mfma_f32_16x16x32_bf16 v[34:37], v[156:159], v[188:191], v[34:37]
	v_mfma_f32_16x16x32_bf16 v[34:37], v[160:163], v[192:195], v[34:37]
	v_mfma_f32_16x16x32_bf16 v[26:29], v[140:143], v[206:209], v[26:29]
	v_mfma_f32_16x16x32_bf16 v[26:29], v[148:151], v[210:213], v[26:29]
	v_mfma_f32_16x16x32_bf16 v[18:21], v[156:159], v[206:209], v[18:21]
	v_mfma_f32_16x16x32_bf16 v[18:21], v[160:163], v[210:213], v[18:21]
	v_mfma_f32_16x16x32_bf16 v[10:13], v[140:143], v[214:217], v[10:13]
	v_mfma_f32_16x16x32_bf16 v[10:13], v[148:151], v[218:221], v[10:13]
	v_mfma_f32_16x16x32_bf16 v[6:9], v[156:159], v[214:217], v[6:9]
	v_mfma_f32_16x16x32_bf16 v[6:9], v[160:163], v[218:221], v[6:9]
	v_mfma_f32_16x16x32_bf16 v[62:65], v[164:167], v[180:183], v[62:65]
	v_mfma_f32_16x16x32_bf16 v[62:65], v[168:171], v[184:187], v[62:65]
	v_mfma_f32_16x16x32_bf16 v[54:57], v[172:175], v[180:183], v[54:57]
	v_mfma_f32_16x16x32_bf16 v[54:57], v[176:179], v[184:187], v[54:57]
	v_mfma_f32_16x16x32_bf16 v[46:49], v[164:167], v[188:191], v[46:49]
	v_mfma_f32_16x16x32_bf16 v[46:49], v[168:171], v[192:195], v[46:49]
	v_mfma_f32_16x16x32_bf16 v[38:41], v[172:175], v[188:191], v[38:41]
	v_mfma_f32_16x16x32_bf16 v[38:41], v[176:179], v[192:195], v[38:41]
	v_mfma_f32_16x16x32_bf16 v[30:33], v[164:167], v[206:209], v[30:33]
	v_mfma_f32_16x16x32_bf16 v[30:33], v[168:171], v[210:213], v[30:33]
	v_mfma_f32_16x16x32_bf16 v[22:25], v[172:175], v[206:209], v[22:25]
	v_mfma_f32_16x16x32_bf16 v[22:25], v[176:179], v[210:213], v[22:25]
	v_mfma_f32_16x16x32_bf16 v[14:17], v[164:167], v[214:217], v[14:17]
	v_mfma_f32_16x16x32_bf16 v[14:17], v[168:171], v[218:221], v[14:17]
	v_mfma_f32_16x16x32_bf16 v[2:5], v[172:175], v[214:217], v[2:5]
	v_mfma_f32_16x16x32_bf16 v[2:5], v[176:179], v[218:221], v[2:5]
	s_barrier
	s_add_i32 s49, s49, 2
	s_add_u32 s26, s26, 0x100
	s_addc_u32 s27, s27, 0
	s_add_u32 s46, s46, 0x100
	s_addc_u32 s47, s47, 0
	s_cmp_gt_u32 s49, 29
	s_cbranch_scc0 .LBB0_168
	s_and_b64 vcc, exec, s[14:15]
	s_cbranch_vccz .LBB0_171
	s_barrier

.LBB0_281:
	s_add_u32 s20, s18, 0x100
	s_addc_u32 s21, s19, 0
	s_add_i32 s2, 0, 0x10000
	s_cmpk_eq_i32 s42, 0x52
	s_cselect_b32 s25, s11, s21
	s_cselect_b32 s24, s10, s20
	s_cselect_b32 s23, s17, s41
	s_cselect_b32 s22, s16, s40
	s_add_u32 s100, s18, 0xffea8000
	s_addc_u32 s101, s19, -1
	s_add_i32 s43, 0, 0x14000
	v_add_u32_e32 v142, s2, v226
	v_add_u32_e32 v160, s43, v226
	s_mov_b32 m0, s36
	ds_read_b128 v[126:129], v142
	ds_read_b128 v[134:137], v142 offset:1024
	ds_read_b128 v[138:141], v142 offset:2048
	ds_read_b128 v[142:145], v142 offset:3072
	global_load_lds_dwordx4 v194, s[100:101]
	s_mov_b32 m0, s37
	ds_read_b128 v[148:151], v160
	ds_read_b128 v[152:155], v160 offset:1024
	ds_read_b128 v[156:159], v160 offset:2048
	ds_read_b128 v[160:163], v160 offset:3072
	global_load_lds_dwordx4 v206, s[100:101]
	s_add_i32 m0, s26, 0xc000
	ds_read_b128 v[164:167], v228
	ds_read_b128 v[168:171], v228 offset:1024
	ds_read_b128 v[172:175], v228 offset:2048
	ds_read_b128 v[176:179], v228 offset:3072
	global_load_lds_dwordx4 v194, s[18:19]
	s_add_i32 m0, s26, 0xe000
	ds_read_b128 v[180:183], v228 offset:4096
	ds_read_b128 v[184:187], v228 offset:5120
	ds_read_b128 v[208:211], v228 offset:6144
	ds_read_b128 v[212:215], v228 offset:7168
	global_load_lds_dwordx4 v206, s[18:19]
	s_waitcnt vmcnt(8)
	s_waitcnt lgkmcnt(0)
	s_barrier
	s_waitcnt lgkmcnt(0)
	v_mfma_f32_16x16x32_bf16 v[130:133], v[126:129], v[164:167], v[130:133]
	v_mfma_f32_16x16x32_bf16 v[130:133], v[134:137], v[168:171], v[130:133]
	v_mfma_f32_16x16x32_bf16 v[122:125], v[138:141], v[164:167], v[122:125]
	v_mfma_f32_16x16x32_bf16 v[122:125], v[142:145], v[168:171], v[122:125]
	v_mfma_f32_16x16x32_bf16 v[110:113], v[126:129], v[172:175], v[110:113]
	v_mfma_f32_16x16x32_bf16 v[110:113], v[134:137], v[176:179], v[110:113]
	v_mfma_f32_16x16x32_bf16 v[106:109], v[138:141], v[172:175], v[106:109]
	v_mfma_f32_16x16x32_bf16 v[106:109], v[142:145], v[176:179], v[106:109]
	v_mfma_f32_16x16x32_bf16 v[94:97], v[126:129], v[180:183], v[94:97]
	v_mfma_f32_16x16x32_bf16 v[94:97], v[134:137], v[184:187], v[94:97]
	v_mfma_f32_16x16x32_bf16 v[90:93], v[138:141], v[180:183], v[90:93]
	v_mfma_f32_16x16x32_bf16 v[90:93], v[142:145], v[184:187], v[90:93]
	v_mfma_f32_16x16x32_bf16 v[78:81], v[126:129], v[208:211], v[78:81]
	v_mfma_f32_16x16x32_bf16 v[78:81], v[134:137], v[212:215], v[78:81]
	v_mfma_f32_16x16x32_bf16 v[74:77], v[138:141], v[208:211], v[74:77]
	v_mfma_f32_16x16x32_bf16 v[74:77], v[142:145], v[212:215], v[74:77]
	v_mfma_f32_16x16x32_bf16 v[118:121], v[148:151], v[164:167], v[118:121]
	v_mfma_f32_16x16x32_bf16 v[118:121], v[152:155], v[168:171], v[118:121]
	v_mfma_f32_16x16x32_bf16 v[114:117], v[156:159], v[164:167], v[114:117]
	v_mfma_f32_16x16x32_bf16 v[114:117], v[160:163], v[168:171], v[114:117]
	v_mfma_f32_16x16x32_bf16 v[102:105], v[148:151], v[172:175], v[102:105]
	v_mfma_f32_16x16x32_bf16 v[102:105], v[152:155], v[176:179], v[102:105]
	v_mfma_f32_16x16x32_bf16 v[98:101], v[156:159], v[172:175], v[98:101]
	v_mfma_f32_16x16x32_bf16 v[98:101], v[160:163], v[176:179], v[98:101]
	v_mfma_f32_16x16x32_bf16 v[86:89], v[148:151], v[180:183], v[86:89]
	v_mfma_f32_16x16x32_bf16 v[86:89], v[152:155], v[184:187], v[86:89]
	v_mfma_f32_16x16x32_bf16 v[82:85], v[156:159], v[180:183], v[82:85]
	v_mfma_f32_16x16x32_bf16 v[82:85], v[160:163], v[184:187], v[82:85]
	v_mfma_f32_16x16x32_bf16 v[70:73], v[148:151], v[208:211], v[70:73]
	v_mfma_f32_16x16x32_bf16 v[70:73], v[152:155], v[212:215], v[70:73]
	v_mfma_f32_16x16x32_bf16 v[66:69], v[156:159], v[208:211], v[66:69]
	v_mfma_f32_16x16x32_bf16 v[66:69], v[160:163], v[212:215], v[66:69]
	s_barrier
	s_add_u32 s18, s22, 0x158000
	s_addc_u32 s19, s23, 0
	s_add_i32 s2, s2, s1
	s_mov_b32 m0, s2
	ds_read_b128 v[164:167], v228 offset:16384
	ds_read_b128 v[168:171], v228 offset:17408
	global_load_lds_dwordx4 v0, s[22:23]
	s_add_i32 m0, s2, 0x2000
	s_add_i32 s2, s43, s1
	ds_read_b128 v[172:175], v228 offset:18432
	ds_read_b128 v[176:179], v228 offset:19456
	global_load_lds_dwordx4 v188, s[22:23]
	s_mov_b32 m0, s2
	ds_read_b128 v[180:183], v228 offset:20480
	ds_read_b128 v[184:187], v228 offset:21504
	global_load_lds_dwordx4 v0, s[18:19]
	s_add_i32 m0, s2, 0x2000
	ds_read_b128 v[208:211], v228 offset:22528
	ds_read_b128 v[212:215], v228 offset:23552
	global_load_lds_dwordx4 v188, s[18:19]
	s_waitcnt vmcnt(6)
	s_waitcnt lgkmcnt(0)
	s_barrier
	s_waitcnt lgkmcnt(0)
	v_mfma_f32_16x16x32_bf16 v[62:65], v[126:129], v[164:167], v[62:65]
	v_mfma_f32_16x16x32_bf16 v[62:65], v[134:137], v[168:171], v[62:65]
	v_mfma_f32_16x16x32_bf16 v[58:61], v[138:141], v[164:167], v[58:61]
	v_mfma_f32_16x16x32_bf16 v[58:61], v[142:145], v[168:171], v[58:61]
	v_mfma_f32_16x16x32_bf16 v[46:49], v[126:129], v[172:175], v[46:49]
	v_mfma_f32_16x16x32_bf16 v[46:49], v[134:137], v[176:179], v[46:49]
	v_mfma_f32_16x16x32_bf16 v[42:45], v[138:141], v[172:175], v[42:45]
	v_mfma_f32_16x16x32_bf16 v[42:45], v[142:145], v[176:179], v[42:45]
	v_mfma_f32_16x16x32_bf16 v[30:33], v[126:129], v[180:183], v[30:33]
	v_mfma_f32_16x16x32_bf16 v[30:33], v[134:137], v[184:187], v[30:33]
	v_mfma_f32_16x16x32_bf16 v[26:29], v[138:141], v[180:183], v[26:29]
	v_mfma_f32_16x16x32_bf16 v[26:29], v[142:145], v[184:187], v[26:29]
	v_mfma_f32_16x16x32_bf16 v[14:17], v[126:129], v[208:211], v[14:17]
	v_mfma_f32_16x16x32_bf16 v[14:17], v[134:137], v[212:215], v[14:17]
	v_mfma_f32_16x16x32_bf16 v[10:13], v[138:141], v[208:211], v[10:13]
	v_mfma_f32_16x16x32_bf16 v[10:13], v[142:145], v[212:215], v[10:13]
	v_mfma_f32_16x16x32_bf16 v[54:57], v[148:151], v[164:167], v[54:57]
	v_mfma_f32_16x16x32_bf16 v[54:57], v[152:155], v[168:171], v[54:57]
	v_mfma_f32_16x16x32_bf16 v[50:53], v[156:159], v[164:167], v[50:53]
	v_mfma_f32_16x16x32_bf16 v[50:53], v[160:163], v[168:171], v[50:53]
	v_mfma_f32_16x16x32_bf16 v[38:41], v[148:151], v[172:175], v[38:41]
	v_mfma_f32_16x16x32_bf16 v[38:41], v[152:155], v[176:179], v[38:41]
	v_mfma_f32_16x16x32_bf16 v[34:37], v[156:159], v[172:175], v[34:37]
	v_mfma_f32_16x16x32_bf16 v[34:37], v[160:163], v[176:179], v[34:37]
	v_mfma_f32_16x16x32_bf16 v[22:25], v[148:151], v[180:183], v[22:25]
	v_mfma_f32_16x16x32_bf16 v[22:25], v[152:155], v[184:187], v[22:25]
	v_mfma_f32_16x16x32_bf16 v[18:21], v[156:159], v[180:183], v[18:21]
	v_mfma_f32_16x16x32_bf16 v[18:21], v[160:163], v[184:187], v[18:21]
	v_mfma_f32_16x16x32_bf16 v[6:9], v[148:151], v[208:211], v[6:9]
	v_mfma_f32_16x16x32_bf16 v[6:9], v[152:155], v[212:215], v[6:9]
	v_mfma_f32_16x16x32_bf16 v[2:5], v[156:159], v[208:211], v[2:5]
	v_mfma_f32_16x16x32_bf16 v[2:5], v[160:163], v[212:215], v[2:5]
	s_barrier
	s_add_u32 s18, s24, 0x158000
	s_addc_u32 s19, s25, 0
	s_add_i32 s2, 0, 0x18000
	s_add_i32 s43, 0, 0x1c000
	v_add_u32_e32 v142, s2, v226
	v_add_u32_e32 v160, s43, v226
	s_mov_b32 m0, s26
	ds_read_b128 v[126:129], v142
	ds_read_b128 v[134:137], v142 offset:1024
	ds_read_b128 v[138:141], v142 offset:2048
	ds_read_b128 v[142:145], v142 offset:3072
	global_load_lds_dwordx4 v192, s[24:25]
	s_mov_b32 m0, s27
	ds_read_b128 v[148:151], v160
	ds_read_b128 v[152:155], v160 offset:1024
	ds_read_b128 v[156:159], v160 offset:2048
	ds_read_b128 v[160:163], v160 offset:3072
	global_load_lds_dwordx4 v190, s[24:25]
	s_mov_b32 m0, s30
	ds_read_b128 v[164:167], v228 offset:32768
	ds_read_b128 v[168:171], v228 offset:33792
	ds_read_b128 v[172:175], v228 offset:34816
	ds_read_b128 v[176:179], v228 offset:35840
	global_load_lds_dwordx4 v192, s[18:19]
	s_mov_b32 m0, s31
	ds_read_b128 v[180:183], v228 offset:36864
	ds_read_b128 v[184:187], v228 offset:37888
	ds_read_b128 v[208:211], v228 offset:38912
	ds_read_b128 v[212:215], v228 offset:39936
	global_load_lds_dwordx4 v190, s[18:19]
	s_waitcnt vmcnt(8)
	s_waitcnt lgkmcnt(0)
	s_barrier
	s_waitcnt lgkmcnt(0)
	v_mfma_f32_16x16x32_bf16 v[130:133], v[126:129], v[164:167], v[130:133]
	v_mfma_f32_16x16x32_bf16 v[130:133], v[134:137], v[168:171], v[130:133]
	v_mfma_f32_16x16x32_bf16 v[122:125], v[138:141], v[164:167], v[122:125]
	v_mfma_f32_16x16x32_bf16 v[122:125], v[142:145], v[168:171], v[122:125]
	v_mfma_f32_16x16x32_bf16 v[110:113], v[126:129], v[172:175], v[110:113]
	v_mfma_f32_16x16x32_bf16 v[110:113], v[134:137], v[176:179], v[110:113]
	v_mfma_f32_16x16x32_bf16 v[106:109], v[138:141], v[172:175], v[106:109]
	v_mfma_f32_16x16x32_bf16 v[106:109], v[142:145], v[176:179], v[106:109]
	v_mfma_f32_16x16x32_bf16 v[94:97], v[126:129], v[180:183], v[94:97]
	v_mfma_f32_16x16x32_bf16 v[94:97], v[134:137], v[184:187], v[94:97]
	v_mfma_f32_16x16x32_bf16 v[90:93], v[138:141], v[180:183], v[90:93]
	v_mfma_f32_16x16x32_bf16 v[90:93], v[142:145], v[184:187], v[90:93]
	v_mfma_f32_16x16x32_bf16 v[78:81], v[126:129], v[208:211], v[78:81]
	v_mfma_f32_16x16x32_bf16 v[78:81], v[134:137], v[212:215], v[78:81]
	v_mfma_f32_16x16x32_bf16 v[74:77], v[138:141], v[208:211], v[74:77]
	v_mfma_f32_16x16x32_bf16 v[74:77], v[142:145], v[212:215], v[74:77]
	v_mfma_f32_16x16x32_bf16 v[118:121], v[148:151], v[164:167], v[118:121]
	v_mfma_f32_16x16x32_bf16 v[118:121], v[152:155], v[168:171], v[118:121]
	v_mfma_f32_16x16x32_bf16 v[114:117], v[156:159], v[164:167], v[114:117]
	v_mfma_f32_16x16x32_bf16 v[114:117], v[160:163], v[168:171], v[114:117]
	v_mfma_f32_16x16x32_bf16 v[102:105], v[148:151], v[172:175], v[102:105]
	v_mfma_f32_16x16x32_bf16 v[102:105], v[152:155], v[176:179], v[102:105]
	v_mfma_f32_16x16x32_bf16 v[98:101], v[156:159], v[172:175], v[98:101]
	v_mfma_f32_16x16x32_bf16 v[98:101], v[160:163], v[176:179], v[98:101]
	v_mfma_f32_16x16x32_bf16 v[86:89], v[148:151], v[180:183], v[86:89]
	v_mfma_f32_16x16x32_bf16 v[86:89], v[152:155], v[184:187], v[86:89]
	v_mfma_f32_16x16x32_bf16 v[82:85], v[156:159], v[180:183], v[82:85]
	v_mfma_f32_16x16x32_bf16 v[82:85], v[160:163], v[184:187], v[82:85]
	v_mfma_f32_16x16x32_bf16 v[70:73], v[148:151], v[208:211], v[70:73]
	v_mfma_f32_16x16x32_bf16 v[70:73], v[152:155], v[212:215], v[70:73]
	v_mfma_f32_16x16x32_bf16 v[66:69], v[156:159], v[208:211], v[66:69]
	v_mfma_f32_16x16x32_bf16 v[66:69], v[160:163], v[212:215], v[66:69]
	s_barrier
	s_add_u32 s18, s22, 0x158080
	s_addc_u32 s19, s23, 0
	s_add_u32 s22, s22, 0x80
	s_addc_u32 s23, s23, 0
	s_add_i32 s2, s2, s1
	s_mov_b32 m0, s2
	ds_read_b128 v[164:167], v228 offset:49152
	ds_read_b128 v[168:171], v228 offset:50176
	global_load_lds_dwordx4 v0, s[22:23]
	s_add_i32 m0, s2, 0x2000
	s_add_i32 s2, s43, s1
	ds_read_b128 v[172:175], v228 offset:51200
	ds_read_b128 v[176:179], v228 offset:52224
	global_load_lds_dwordx4 v188, s[22:23]
	s_mov_b32 m0, s2
	ds_read_b128 v[180:183], v228 offset:53248
	ds_read_b128 v[184:187], v228 offset:54272
	global_load_lds_dwordx4 v0, s[18:19]
	s_add_i32 m0, s2, 0x2000
	ds_read_b128 v[208:211], v228 offset:55296
	ds_read_b128 v[212:215], v228 offset:56320
	global_load_lds_dwordx4 v188, s[18:19]
	s_waitcnt vmcnt(6)
	s_waitcnt lgkmcnt(0)
	s_barrier
	s_waitcnt lgkmcnt(0)
	v_mfma_f32_16x16x32_bf16 v[62:65], v[126:129], v[164:167], v[62:65]
	v_mfma_f32_16x16x32_bf16 v[62:65], v[134:137], v[168:171], v[62:65]
	v_mfma_f32_16x16x32_bf16 v[58:61], v[138:141], v[164:167], v[58:61]
	v_mfma_f32_16x16x32_bf16 v[58:61], v[142:145], v[168:171], v[58:61]
	v_mfma_f32_16x16x32_bf16 v[46:49], v[126:129], v[172:175], v[46:49]
	v_mfma_f32_16x16x32_bf16 v[46:49], v[134:137], v[176:179], v[46:49]
	v_mfma_f32_16x16x32_bf16 v[42:45], v[138:141], v[172:175], v[42:45]
	v_mfma_f32_16x16x32_bf16 v[42:45], v[142:145], v[176:179], v[42:45]
	v_mfma_f32_16x16x32_bf16 v[30:33], v[126:129], v[180:183], v[30:33]
	v_mfma_f32_16x16x32_bf16 v[30:33], v[134:137], v[184:187], v[30:33]
	v_mfma_f32_16x16x32_bf16 v[26:29], v[138:141], v[180:183], v[26:29]
	v_mfma_f32_16x16x32_bf16 v[26:29], v[142:145], v[184:187], v[26:29]
	v_mfma_f32_16x16x32_bf16 v[14:17], v[126:129], v[208:211], v[14:17]
	v_mfma_f32_16x16x32_bf16 v[14:17], v[134:137], v[212:215], v[14:17]
	v_mfma_f32_16x16x32_bf16 v[10:13], v[138:141], v[208:211], v[10:13]
	v_mfma_f32_16x16x32_bf16 v[10:13], v[142:145], v[212:215], v[10:13]
	v_mfma_f32_16x16x32_bf16 v[54:57], v[148:151], v[164:167], v[54:57]
	v_mfma_f32_16x16x32_bf16 v[54:57], v[152:155], v[168:171], v[54:57]
	v_mfma_f32_16x16x32_bf16 v[50:53], v[156:159], v[164:167], v[50:53]
	v_mfma_f32_16x16x32_bf16 v[50:53], v[160:163], v[168:171], v[50:53]
	v_mfma_f32_16x16x32_bf16 v[38:41], v[148:151], v[172:175], v[38:41]
	v_mfma_f32_16x16x32_bf16 v[38:41], v[152:155], v[176:179], v[38:41]
	v_mfma_f32_16x16x32_bf16 v[34:37], v[156:159], v[172:175], v[34:37]
	v_mfma_f32_16x16x32_bf16 v[34:37], v[160:163], v[176:179], v[34:37]
	v_mfma_f32_16x16x32_bf16 v[22:25], v[148:151], v[180:183], v[22:25]
	v_mfma_f32_16x16x32_bf16 v[22:25], v[152:155], v[184:187], v[22:25]
	v_mfma_f32_16x16x32_bf16 v[18:21], v[156:159], v[180:183], v[18:21]
	v_mfma_f32_16x16x32_bf16 v[18:21], v[160:163], v[184:187], v[18:21]
	v_mfma_f32_16x16x32_bf16 v[6:9], v[148:151], v[208:211], v[6:9]
	v_mfma_f32_16x16x32_bf16 v[6:9], v[152:155], v[212:215], v[6:9]
	v_mfma_f32_16x16x32_bf16 v[2:5], v[156:159], v[208:211], v[2:5]
	v_mfma_f32_16x16x32_bf16 v[2:5], v[160:163], v[212:215], v[2:5]
	s_barrier
	s_add_i32 s42, s42, 2
	s_add_u32 s40, s40, 0x100
	s_addc_u32 s41, s41, 0
	s_cmpk_gt_u32 s42, 0x53
	s_mov_b64 s[18:19], s[20:21]
	s_cbranch_scc0 .LBB0_281
	s_nop 0
	s_nop 0
	s_nop 0
	v_lshl_or_b32 v210, s3, 8, v227
	v_lshl_add_u32 v224, s34, 8, v147
	v_ashrrev_i32_e32 v211, 31, v210
	v_lshlrev_b64 v[126:127], 1, v[210:211]
	v_ashrrev_i32_e32 v225, 31, v224
	v_lshl_add_u64 v[128:129], s[12:13], 0, v[126:127]
	v_lshlrev_b64 v[134:135], 12, v[224:225]
	v_lshl_add_u64 v[136:137], v[128:129], 0, v[134:135]
	global_load_dwordx4 v[240:243], v[136:137], off
	global_load_dwordx4 v[244:247], v[136:137], off offset:256
	v_or_b32_e32 v222, 16, v224
	v_or_b32_e32 v220, 32, v224
	v_or_b32_e32 v218, 48, v224
	v_add_u32_e32 v216, 0x80, v224
	v_add_u32_e32 v214, 0x90, v224
	v_add_u32_e32 v212, 0xa0, v224
	v_add_u32_e32 v208, 0xb0, v224
	v_ashrrev_i32_e32 v223, 31, v222
	v_ashrrev_i32_e32 v221, 31, v220
	v_ashrrev_i32_e32 v219, 31, v218
	v_ashrrev_i32_e32 v217, 31, v216
	v_ashrrev_i32_e32 v215, 31, v214
	v_ashrrev_i32_e32 v213, 31, v212
	v_ashrrev_i32_e32 v209, 31, v208
	v_lshlrev_b64 v[136:137], 12, v[222:223]
	v_lshlrev_b64 v[138:139], 12, v[220:221]
	v_lshlrev_b64 v[140:141], 12, v[218:219]
	v_lshlrev_b64 v[142:143], 12, v[216:217]
	v_lshlrev_b64 v[144:145], 12, v[214:215]
	v_lshlrev_b64 v[148:149], 12, v[212:213]
	v_lshlrev_b64 v[150:151], 12, v[208:209]
	v_lshl_add_u64 v[134:135], s[12:13], 0, v[134:135]
	v_lshl_add_u64 v[136:137], v[128:129], 0, v[136:137]
	v_lshl_add_u64 v[138:139], v[128:129], 0, v[138:139]
	v_lshl_add_u64 v[140:141], v[128:129], 0, v[140:141]
	v_lshl_add_u64 v[142:143], v[128:129], 0, v[142:143]
	v_lshl_add_u64 v[144:145], v[128:129], 0, v[144:145]
	v_lshl_add_u64 v[248:249], v[128:129], 0, v[148:149]
	v_lshl_add_u64 v[128:129], v[128:129], 0, v[150:151]
	v_lshl_add_u64 v[250:251], v[134:135], 0, v[126:127]
	global_load_dwordx4 v[184:187], v[136:137], off
	global_load_dwordx4 v[180:183], v[136:137], off offset:256
	global_load_dwordx4 v[176:179], v[138:139], off
	global_load_dwordx4 v[172:175], v[138:139], off offset:256
	global_load_dwordx4 v[168:171], v[140:141], off
	global_load_dwordx4 v[164:167], v[140:141], off offset:256
	global_load_dwordx4 v[160:163], v[142:143], off
	global_load_dwordx4 v[156:159], v[142:143], off offset:256
	global_load_dwordx4 v[152:155], v[144:145], off
	global_load_dwordx4 v[148:151], v[144:145], off offset:256
	s_nop 0
	global_load_dwordx4 v[142:145], v[248:249], off
	global_load_dwordx4 v[138:141], v[248:249], off offset:256
	global_load_dwordx4 v[134:137], v[128:129], off
	s_nop 0
	global_load_dwordx4 v[126:129], v[128:129], off offset:256
	s_lshl_b32 s18, s3, 2
	s_ashr_i32 s19, s18, 31
	s_waitcnt vmcnt(0)
	v_lshlrev_b32_e32 v248, 16, v240
	v_and_b32_e32 v249, 0xffff0000, v240
	v_lshlrev_b32_e32 v240, 16, v241
	v_and_b32_e32 v241, 0xffff0000, v241
	v_lshlrev_b32_e32 v252, 16, v242
	v_and_b32_e32 v253, 0xffff0000, v242
	v_lshlrev_b32_e32 v242, 16, v243
	v_and_b32_e32 v243, 0xffff0000, v243
	v_pk_fma_f32 v[132:133], v[132:133], 0.5, v[240:241] op_sel_hi:[1,0,1]
	v_pk_fma_f32 v[240:241], v[124:125], 0.5, v[242:243] op_sel_hi:[1,0,1]
	v_pk_fma_f32 v[124:125], v[122:123], 0.5, v[252:253] op_sel_hi:[1,0,1]
	v_pk_fma_f32 v[130:131], v[130:131], 0.5, v[248:249] op_sel_hi:[1,0,1]
	v_lshlrev_b32_e32 v236, 16, v244
	v_cvt_pk_bf16_f32 v122, v130, v131
	v_cvt_pk_bf16_f32 v123, v132, v133
	v_cvt_pk_bf16_f32 v124, v124, v125
	v_cvt_pk_bf16_f32 v125, v240, v241
	global_store_dwordx4 v[250:251], v[122:125], off
	v_lshlrev_b32_e32 v130, 16, v122
	v_lshlrev_b32_e32 v131, 16, v123
	v_and_b32_e32 v122, 0xffff0000, v122
	v_and_b32_e32 v123, 0xffff0000, v123
	v_lshlrev_b32_e32 v132, 16, v124
	v_and_b32_e32 v124, 0xffff0000, v124
	v_lshlrev_b32_e32 v133, 16, v125
	v_and_b32_e32 v125, 0xffff0000, v125
	v_mul_f32_e32 v122, v122, v122
	v_mul_f32_e32 v123, v123, v123
	v_mul_f32_e32 v124, v124, v124
	v_mul_f32_e32 v125, v125, v125
	v_fmac_f32_e32 v122, v130, v130
	v_fmac_f32_e32 v123, v131, v131
	v_fmac_f32_e32 v124, v132, v132
	v_fmac_f32_e32 v125, v133, v133
	v_add_f32_e32 v122, v122, v123
	v_add_f32_e32 v123, v124, v125
	v_and_b32_e32 v237, 0xffff0000, v244
	v_add_f32_e32 v132, v122, v123
	v_lshlrev_b32_e32 v122, 16, v245
	v_and_b32_e32 v123, 0xffff0000, v245
	v_lshlrev_b32_e32 v124, 16, v246
	v_and_b32_e32 v125, 0xffff0000, v246
	v_lshlrev_b32_e32 v130, 16, v247
	v_and_b32_e32 v131, 0xffff0000, v247
	v_pk_fma_f32 v[120:121], v[120:121], 0.5, v[122:123] op_sel_hi:[1,0,1]
	v_pk_fma_f32 v[118:119], v[118:119], 0.5, v[236:237] op_sel_hi:[1,0,1]
	v_pk_fma_f32 v[122:123], v[116:117], 0.5, v[130:131] op_sel_hi:[1,0,1]
	v_pk_fma_f32 v[116:117], v[114:115], 0.5, v[124:125] op_sel_hi:[1,0,1]
	v_cvt_pk_bf16_f32 v114, v118, v119
	v_cvt_pk_bf16_f32 v115, v120, v121
	s_nop 0
	v_cvt_pk_bf16_f32 v116, v116, v117
	v_cvt_pk_bf16_f32 v117, v122, v123
	global_store_dwordx4 v[250:251], v[114:117], off offset:256
	v_lshlrev_b32_e32 v118, 16, v114
	v_lshlrev_b32_e32 v119, 16, v115
	v_and_b32_e32 v114, 0xffff0000, v114
	v_and_b32_e32 v115, 0xffff0000, v115
	v_mul_f32_e32 v114, v114, v114
	v_mul_f32_e32 v115, v115, v115
	v_lshlrev_b32_e32 v120, 16, v116
	v_and_b32_e32 v116, 0xffff0000, v116
	v_lshlrev_b32_e32 v121, 16, v117
	v_and_b32_e32 v117, 0xffff0000, v117
	v_fmac_f32_e32 v114, v118, v118
	v_fmac_f32_e32 v115, v119, v119
	v_add_f32_e32 v114, v114, v115
	v_mul_f32_e32 v115, v116, v116
	v_mul_f32_e32 v116, v117, v117
	v_fmac_f32_e32 v115, v120, v120
	v_fmac_f32_e32 v116, v121, v121
	v_add_f32_e32 v115, v115, v116
	v_add_f32_e32 v114, v114, v115
	s_mov_b32 s2, 0
	v_add_f32_e32 v114, v132, v114
	v_mbcnt_lo_u32_b32 v115, -1, s2
	v_mbcnt_hi_u32_b32 v115, -1, v115
	v_lshlrev_b32_e32 v115, 2, v115
	v_xor_b32_e32 v115, 64, v115
	ds_bpermute_b32 v115, v115, v114
	s_mov_b32 s2, 0
	s_waitcnt lgkmcnt(0)
	v_add_f32_e32 v114, v114, v115
	v_mbcnt_lo_u32_b32 v115, -1, s2
	v_mbcnt_hi_u32_b32 v115, -1, v115
	v_lshlrev_b32_e32 v115, 2, v115
	v_xor_b32_e32 v115, 0x80, v115
	ds_bpermute_b32 v115, v115, v114
	s_and_saveexec_b64 s[20:21], s[6:7]
	s_cbranch_execz .LBB0_284
	v_lshlrev_b64 v[116:117], 7, v[224:225]
	v_lshl_add_u64 v[116:117], s[14:15], 0, v[116:117]
	v_lshl_add_u64 v[116:117], s[18:19], 2, v[116:117]
	s_lshl_b32 s50, s35, 2
	v_lshl_add_u64 v[116:117], v[116:117], 0, s[50:51]
	s_waitcnt lgkmcnt(0)
	v_add_f32_e32 v114, v114, v115
	global_store_dword v[116:117], v114, off

.LBB0_322:
	s_add_u32 s22, s20, 0x100
	s_addc_u32 s23, s21, 0
	s_add_i32 s2, 0, 0x10000
	s_cmpk_eq_i32 s42, 0x52
	s_cselect_b32 s27, s9, s23
	s_cselect_b32 s26, s8, s22
	s_cselect_b32 s25, s19, s41
	s_cselect_b32 s24, s18, s40
	s_add_u32 s100, s20, 0xffea8000
	s_addc_u32 s101, s21, -1
	s_add_i32 s43, 0, 0x14000
	v_add_u32_e32 v142, s2, v240
	v_add_u32_e32 v160, s43, v240
	s_mov_b32 m0, s35
	ds_read_b128 v[130:133], v142
	ds_read_b128 v[134:137], v142 offset:1024
	ds_read_b128 v[138:141], v142 offset:2048
	ds_read_b128 v[142:145], v142 offset:3072
	global_load_lds_dwordx4 v208, s[100:101]
	s_mov_b32 m0, s36
	ds_read_b128 v[148:151], v160
	ds_read_b128 v[152:155], v160 offset:1024
	ds_read_b128 v[156:159], v160 offset:2048
	ds_read_b128 v[160:163], v160 offset:3072
	global_load_lds_dwordx4 v210, s[100:101]
	s_add_i32 m0, s1, 0xc000
	ds_read_b128 v[164:167], v242
	ds_read_b128 v[168:171], v242 offset:1024
	ds_read_b128 v[172:175], v242 offset:2048
	ds_read_b128 v[176:179], v242 offset:3072
	global_load_lds_dwordx4 v208, s[20:21]
	s_add_i32 m0, s1, 0xe000
	ds_read_b128 v[180:183], v242 offset:4096
	ds_read_b128 v[184:187], v242 offset:5120
	ds_read_b128 v[188:191], v242 offset:6144
	ds_read_b128 v[212:215], v242 offset:7168
	global_load_lds_dwordx4 v210, s[20:21]
	s_waitcnt vmcnt(8)
	s_waitcnt lgkmcnt(0)
	s_barrier
	s_waitcnt lgkmcnt(0)
	v_mfma_f32_16x16x32_bf16 v[126:129], v[130:133], v[164:167], v[126:129]
	v_mfma_f32_16x16x32_bf16 v[126:129], v[134:137], v[168:171], v[126:129]
	v_mfma_f32_16x16x32_bf16 v[122:125], v[138:141], v[164:167], v[122:125]
	v_mfma_f32_16x16x32_bf16 v[122:125], v[142:145], v[168:171], v[122:125]
	v_mfma_f32_16x16x32_bf16 v[110:113], v[130:133], v[172:175], v[110:113]
	v_mfma_f32_16x16x32_bf16 v[110:113], v[134:137], v[176:179], v[110:113]
	v_mfma_f32_16x16x32_bf16 v[106:109], v[138:141], v[172:175], v[106:109]
	v_mfma_f32_16x16x32_bf16 v[106:109], v[142:145], v[176:179], v[106:109]
	v_mfma_f32_16x16x32_bf16 v[94:97], v[130:133], v[180:183], v[94:97]
	v_mfma_f32_16x16x32_bf16 v[94:97], v[134:137], v[184:187], v[94:97]
	v_mfma_f32_16x16x32_bf16 v[90:93], v[138:141], v[180:183], v[90:93]
	v_mfma_f32_16x16x32_bf16 v[90:93], v[142:145], v[184:187], v[90:93]
	v_mfma_f32_16x16x32_bf16 v[78:81], v[130:133], v[188:191], v[78:81]
	v_mfma_f32_16x16x32_bf16 v[78:81], v[134:137], v[212:215], v[78:81]
	v_mfma_f32_16x16x32_bf16 v[74:77], v[138:141], v[188:191], v[74:77]
	v_mfma_f32_16x16x32_bf16 v[74:77], v[142:145], v[212:215], v[74:77]
	v_mfma_f32_16x16x32_bf16 v[118:121], v[148:151], v[164:167], v[118:121]
	v_mfma_f32_16x16x32_bf16 v[118:121], v[152:155], v[168:171], v[118:121]
	v_mfma_f32_16x16x32_bf16 v[114:117], v[156:159], v[164:167], v[114:117]
	v_mfma_f32_16x16x32_bf16 v[114:117], v[160:163], v[168:171], v[114:117]
	v_mfma_f32_16x16x32_bf16 v[102:105], v[148:151], v[172:175], v[102:105]
	v_mfma_f32_16x16x32_bf16 v[102:105], v[152:155], v[176:179], v[102:105]
	v_mfma_f32_16x16x32_bf16 v[98:101], v[156:159], v[172:175], v[98:101]
	v_mfma_f32_16x16x32_bf16 v[98:101], v[160:163], v[176:179], v[98:101]
	v_mfma_f32_16x16x32_bf16 v[86:89], v[148:151], v[180:183], v[86:89]
	v_mfma_f32_16x16x32_bf16 v[86:89], v[152:155], v[184:187], v[86:89]
	v_mfma_f32_16x16x32_bf16 v[82:85], v[156:159], v[180:183], v[82:85]
	v_mfma_f32_16x16x32_bf16 v[82:85], v[160:163], v[184:187], v[82:85]
	v_mfma_f32_16x16x32_bf16 v[70:73], v[148:151], v[188:191], v[70:73]
	v_mfma_f32_16x16x32_bf16 v[70:73], v[152:155], v[212:215], v[70:73]
	v_mfma_f32_16x16x32_bf16 v[66:69], v[156:159], v[188:191], v[66:69]
	v_mfma_f32_16x16x32_bf16 v[66:69], v[160:163], v[212:215], v[66:69]
	s_barrier
	s_add_u32 s20, s24, 0x158000
	s_addc_u32 s21, s25, 0
	s_add_i32 s2, s2, s0
	s_mov_b32 m0, s2
	ds_read_b128 v[164:167], v242 offset:16384
	ds_read_b128 v[168:171], v242 offset:17408
	global_load_lds_dwordx4 v0, s[24:25]
	s_add_i32 m0, s2, 0x2000
	s_add_i32 s2, s43, s0
	ds_read_b128 v[172:175], v242 offset:18432
	ds_read_b128 v[176:179], v242 offset:19456
	global_load_lds_dwordx4 v192, s[24:25]
	s_mov_b32 m0, s2
	ds_read_b128 v[180:183], v242 offset:20480
	ds_read_b128 v[184:187], v242 offset:21504
	global_load_lds_dwordx4 v0, s[20:21]
	s_add_i32 m0, s2, 0x2000
	ds_read_b128 v[188:191], v242 offset:22528
	ds_read_b128 v[212:215], v242 offset:23552
	global_load_lds_dwordx4 v192, s[20:21]
	s_waitcnt vmcnt(6)
	s_waitcnt lgkmcnt(0)
	s_barrier
	s_waitcnt lgkmcnt(0)
	v_mfma_f32_16x16x32_bf16 v[62:65], v[130:133], v[164:167], v[62:65]
	v_mfma_f32_16x16x32_bf16 v[62:65], v[134:137], v[168:171], v[62:65]
	v_mfma_f32_16x16x32_bf16 v[58:61], v[138:141], v[164:167], v[58:61]
	v_mfma_f32_16x16x32_bf16 v[58:61], v[142:145], v[168:171], v[58:61]
	v_mfma_f32_16x16x32_bf16 v[46:49], v[130:133], v[172:175], v[46:49]
	v_mfma_f32_16x16x32_bf16 v[46:49], v[134:137], v[176:179], v[46:49]
	v_mfma_f32_16x16x32_bf16 v[42:45], v[138:141], v[172:175], v[42:45]
	v_mfma_f32_16x16x32_bf16 v[42:45], v[142:145], v[176:179], v[42:45]
	v_mfma_f32_16x16x32_bf16 v[30:33], v[130:133], v[180:183], v[30:33]
	v_mfma_f32_16x16x32_bf16 v[30:33], v[134:137], v[184:187], v[30:33]
	v_mfma_f32_16x16x32_bf16 v[26:29], v[138:141], v[180:183], v[26:29]
	v_mfma_f32_16x16x32_bf16 v[26:29], v[142:145], v[184:187], v[26:29]
	v_mfma_f32_16x16x32_bf16 v[14:17], v[130:133], v[188:191], v[14:17]
	v_mfma_f32_16x16x32_bf16 v[14:17], v[134:137], v[212:215], v[14:17]
	v_mfma_f32_16x16x32_bf16 v[10:13], v[138:141], v[188:191], v[10:13]
	v_mfma_f32_16x16x32_bf16 v[10:13], v[142:145], v[212:215], v[10:13]
	v_mfma_f32_16x16x32_bf16 v[54:57], v[148:151], v[164:167], v[54:57]
	v_mfma_f32_16x16x32_bf16 v[54:57], v[152:155], v[168:171], v[54:57]
	v_mfma_f32_16x16x32_bf16 v[50:53], v[156:159], v[164:167], v[50:53]
	v_mfma_f32_16x16x32_bf16 v[50:53], v[160:163], v[168:171], v[50:53]
	v_mfma_f32_16x16x32_bf16 v[38:41], v[148:151], v[172:175], v[38:41]
	v_mfma_f32_16x16x32_bf16 v[38:41], v[152:155], v[176:179], v[38:41]
	v_mfma_f32_16x16x32_bf16 v[34:37], v[156:159], v[172:175], v[34:37]
	v_mfma_f32_16x16x32_bf16 v[34:37], v[160:163], v[176:179], v[34:37]
	v_mfma_f32_16x16x32_bf16 v[22:25], v[148:151], v[180:183], v[22:25]
	v_mfma_f32_16x16x32_bf16 v[22:25], v[152:155], v[184:187], v[22:25]
	v_mfma_f32_16x16x32_bf16 v[18:21], v[156:159], v[180:183], v[18:21]
	v_mfma_f32_16x16x32_bf16 v[18:21], v[160:163], v[184:187], v[18:21]
	v_mfma_f32_16x16x32_bf16 v[6:9], v[148:151], v[188:191], v[6:9]
	v_mfma_f32_16x16x32_bf16 v[6:9], v[152:155], v[212:215], v[6:9]
	v_mfma_f32_16x16x32_bf16 v[2:5], v[156:159], v[188:191], v[2:5]
	v_mfma_f32_16x16x32_bf16 v[2:5], v[160:163], v[212:215], v[2:5]
	s_barrier
	s_add_u32 s20, s26, 0x158000
	s_addc_u32 s21, s27, 0
	s_add_i32 s2, 0, 0x18000
	s_add_i32 s43, 0, 0x1c000
	v_add_u32_e32 v142, s2, v240
	v_add_u32_e32 v160, s43, v240
	s_mov_b32 m0, s1
	ds_read_b128 v[130:133], v142
	ds_read_b128 v[134:137], v142 offset:1024
	ds_read_b128 v[138:141], v142 offset:2048
	ds_read_b128 v[142:145], v142 offset:3072
	global_load_lds_dwordx4 v206, s[26:27]
	s_mov_b32 m0, s30
	ds_read_b128 v[148:151], v160
	ds_read_b128 v[152:155], v160 offset:1024
	ds_read_b128 v[156:159], v160 offset:2048
	ds_read_b128 v[160:163], v160 offset:3072
	global_load_lds_dwordx4 v194, s[26:27]
	s_mov_b32 m0, s31
	ds_read_b128 v[164:167], v242 offset:32768
	ds_read_b128 v[168:171], v242 offset:33792
	ds_read_b128 v[172:175], v242 offset:34816
	ds_read_b128 v[176:179], v242 offset:35840
	global_load_lds_dwordx4 v206, s[20:21]
	s_mov_b32 m0, s33
	ds_read_b128 v[180:183], v242 offset:36864
	ds_read_b128 v[184:187], v242 offset:37888
	ds_read_b128 v[188:191], v242 offset:38912
	ds_read_b128 v[212:215], v242 offset:39936
	global_load_lds_dwordx4 v194, s[20:21]
	s_waitcnt vmcnt(8)
	s_waitcnt lgkmcnt(0)
	s_barrier
	s_waitcnt lgkmcnt(0)
	v_mfma_f32_16x16x32_bf16 v[126:129], v[130:133], v[164:167], v[126:129]
	v_mfma_f32_16x16x32_bf16 v[126:129], v[134:137], v[168:171], v[126:129]
	v_mfma_f32_16x16x32_bf16 v[122:125], v[138:141], v[164:167], v[122:125]
	v_mfma_f32_16x16x32_bf16 v[122:125], v[142:145], v[168:171], v[122:125]
	v_mfma_f32_16x16x32_bf16 v[110:113], v[130:133], v[172:175], v[110:113]
	v_mfma_f32_16x16x32_bf16 v[110:113], v[134:137], v[176:179], v[110:113]
	v_mfma_f32_16x16x32_bf16 v[106:109], v[138:141], v[172:175], v[106:109]
	v_mfma_f32_16x16x32_bf16 v[106:109], v[142:145], v[176:179], v[106:109]
	v_mfma_f32_16x16x32_bf16 v[94:97], v[130:133], v[180:183], v[94:97]
	v_mfma_f32_16x16x32_bf16 v[94:97], v[134:137], v[184:187], v[94:97]
	v_mfma_f32_16x16x32_bf16 v[90:93], v[138:141], v[180:183], v[90:93]
	v_mfma_f32_16x16x32_bf16 v[90:93], v[142:145], v[184:187], v[90:93]
	v_mfma_f32_16x16x32_bf16 v[78:81], v[130:133], v[188:191], v[78:81]
	v_mfma_f32_16x16x32_bf16 v[78:81], v[134:137], v[212:215], v[78:81]
	v_mfma_f32_16x16x32_bf16 v[74:77], v[138:141], v[188:191], v[74:77]
	v_mfma_f32_16x16x32_bf16 v[74:77], v[142:145], v[212:215], v[74:77]
	v_mfma_f32_16x16x32_bf16 v[118:121], v[148:151], v[164:167], v[118:121]
	v_mfma_f32_16x16x32_bf16 v[118:121], v[152:155], v[168:171], v[118:121]
	v_mfma_f32_16x16x32_bf16 v[114:117], v[156:159], v[164:167], v[114:117]
	v_mfma_f32_16x16x32_bf16 v[114:117], v[160:163], v[168:171], v[114:117]
	v_mfma_f32_16x16x32_bf16 v[102:105], v[148:151], v[172:175], v[102:105]
	v_mfma_f32_16x16x32_bf16 v[102:105], v[152:155], v[176:179], v[102:105]
	v_mfma_f32_16x16x32_bf16 v[98:101], v[156:159], v[172:175], v[98:101]
	v_mfma_f32_16x16x32_bf16 v[98:101], v[160:163], v[176:179], v[98:101]
	v_mfma_f32_16x16x32_bf16 v[86:89], v[148:151], v[180:183], v[86:89]
	v_mfma_f32_16x16x32_bf16 v[86:89], v[152:155], v[184:187], v[86:89]
	v_mfma_f32_16x16x32_bf16 v[82:85], v[156:159], v[180:183], v[82:85]
	v_mfma_f32_16x16x32_bf16 v[82:85], v[160:163], v[184:187], v[82:85]
	v_mfma_f32_16x16x32_bf16 v[70:73], v[148:151], v[188:191], v[70:73]
	v_mfma_f32_16x16x32_bf16 v[70:73], v[152:155], v[212:215], v[70:73]
	v_mfma_f32_16x16x32_bf16 v[66:69], v[156:159], v[188:191], v[66:69]
	v_mfma_f32_16x16x32_bf16 v[66:69], v[160:163], v[212:215], v[66:69]
	s_barrier
	s_add_u32 s20, s24, 0x158080
	s_addc_u32 s21, s25, 0
	s_add_u32 s24, s24, 0x80
	s_addc_u32 s25, s25, 0
	s_add_i32 s2, s2, s0
	s_mov_b32 m0, s2
	ds_read_b128 v[164:167], v242 offset:49152
	ds_read_b128 v[168:171], v242 offset:50176
	global_load_lds_dwordx4 v0, s[24:25]
	s_add_i32 m0, s2, 0x2000
	s_add_i32 s2, s43, s0
	ds_read_b128 v[172:175], v242 offset:51200
	ds_read_b128 v[176:179], v242 offset:52224
	global_load_lds_dwordx4 v192, s[24:25]
	s_mov_b32 m0, s2
	ds_read_b128 v[180:183], v242 offset:53248
	ds_read_b128 v[184:187], v242 offset:54272
	global_load_lds_dwordx4 v0, s[20:21]
	s_add_i32 m0, s2, 0x2000
	ds_read_b128 v[188:191], v242 offset:55296
	ds_read_b128 v[212:215], v242 offset:56320
	global_load_lds_dwordx4 v192, s[20:21]
	s_waitcnt vmcnt(6)
	s_waitcnt lgkmcnt(0)
	s_barrier
	s_waitcnt lgkmcnt(0)
	v_mfma_f32_16x16x32_bf16 v[62:65], v[130:133], v[164:167], v[62:65]
	v_mfma_f32_16x16x32_bf16 v[62:65], v[134:137], v[168:171], v[62:65]
	v_mfma_f32_16x16x32_bf16 v[58:61], v[138:141], v[164:167], v[58:61]
	v_mfma_f32_16x16x32_bf16 v[58:61], v[142:145], v[168:171], v[58:61]
	v_mfma_f32_16x16x32_bf16 v[46:49], v[130:133], v[172:175], v[46:49]
	v_mfma_f32_16x16x32_bf16 v[46:49], v[134:137], v[176:179], v[46:49]
	v_mfma_f32_16x16x32_bf16 v[42:45], v[138:141], v[172:175], v[42:45]
	v_mfma_f32_16x16x32_bf16 v[42:45], v[142:145], v[176:179], v[42:45]
	v_mfma_f32_16x16x32_bf16 v[30:33], v[130:133], v[180:183], v[30:33]
	v_mfma_f32_16x16x32_bf16 v[30:33], v[134:137], v[184:187], v[30:33]
	v_mfma_f32_16x16x32_bf16 v[26:29], v[138:141], v[180:183], v[26:29]
	v_mfma_f32_16x16x32_bf16 v[26:29], v[142:145], v[184:187], v[26:29]
	v_mfma_f32_16x16x32_bf16 v[14:17], v[130:133], v[188:191], v[14:17]
	v_mfma_f32_16x16x32_bf16 v[14:17], v[134:137], v[212:215], v[14:17]
	v_mfma_f32_16x16x32_bf16 v[10:13], v[138:141], v[188:191], v[10:13]
	v_mfma_f32_16x16x32_bf16 v[10:13], v[142:145], v[212:215], v[10:13]
	v_mfma_f32_16x16x32_bf16 v[54:57], v[148:151], v[164:167], v[54:57]
	v_mfma_f32_16x16x32_bf16 v[54:57], v[152:155], v[168:171], v[54:57]
	v_mfma_f32_16x16x32_bf16 v[50:53], v[156:159], v[164:167], v[50:53]
	v_mfma_f32_16x16x32_bf16 v[50:53], v[160:163], v[168:171], v[50:53]
	v_mfma_f32_16x16x32_bf16 v[38:41], v[148:151], v[172:175], v[38:41]
	v_mfma_f32_16x16x32_bf16 v[38:41], v[152:155], v[176:179], v[38:41]
	v_mfma_f32_16x16x32_bf16 v[34:37], v[156:159], v[172:175], v[34:37]
	v_mfma_f32_16x16x32_bf16 v[34:37], v[160:163], v[176:179], v[34:37]
	v_mfma_f32_16x16x32_bf16 v[22:25], v[148:151], v[180:183], v[22:25]
	v_mfma_f32_16x16x32_bf16 v[22:25], v[152:155], v[184:187], v[22:25]
	v_mfma_f32_16x16x32_bf16 v[18:21], v[156:159], v[180:183], v[18:21]
	v_mfma_f32_16x16x32_bf16 v[18:21], v[160:163], v[184:187], v[18:21]
	v_mfma_f32_16x16x32_bf16 v[6:9], v[148:151], v[188:191], v[6:9]
	v_mfma_f32_16x16x32_bf16 v[6:9], v[152:155], v[212:215], v[6:9]
	v_mfma_f32_16x16x32_bf16 v[2:5], v[156:159], v[188:191], v[2:5]
	v_mfma_f32_16x16x32_bf16 v[2:5], v[160:163], v[212:215], v[2:5]
	s_barrier
	s_add_i32 s42, s42, 2
	s_add_u32 s40, s40, 0x100
	s_addc_u32 s41, s41, 0
	s_cmpk_gt_u32 s42, 0x53
	s_mov_b64 s[20:21], s[22:23]
	s_cbranch_scc0 .LBB0_322
	s_nop 0
	s_nop 0
	s_nop 0
	s_and_b64 vcc, exec, s[16:17]
	s_cbranch_vccz .LBB0_325
	s_barrier

.LBB0_408:
	s_add_u32 s2, s24, 0xfff80080
	s_addc_u32 s22, s25, -1
	s_add_i32 s45, 0, 0x10000
	s_cmp_eq_u32 s44, 28
	s_cselect_b32 s27, s17, s22
	s_cselect_b32 s26, s40, s2
	v_add_u32_e32 v144, s45, v148
	s_cselect_b32 s23, s15, s43
	s_cselect_b32 s22, s41, s42
	s_add_u32 s100, s24, 0xfff80000
	s_addc_u32 s101, s25, -1
	s_add_i32 s2, 0, 0x14000
	s_mov_b32 m0, s35
	ds_read_b128 v[140:143], v144
	ds_read_b128 v[152:155], v144 offset:1024
	ds_read_b128 v[156:159], v144 offset:2048
	ds_read_b128 v[160:163], v144 offset:3072
	global_load_lds_dwordx4 v136, s[100:101]
	s_mov_b32 m0, s36
	v_add_u32_e32 v144, s2, v148
	ds_read_b128 v[164:167], v144
	ds_read_b128 v[168:171], v144 offset:1024
	ds_read_b128 v[172:175], v144 offset:2048
	ds_read_b128 v[176:179], v144 offset:3072
	global_load_lds_dwordx4 v138, s[100:101]
	s_add_i32 m0, s29, 0xc000
	ds_read_b128 v[180:183], v151
	ds_read_b128 v[184:187], v151 offset:1024
	ds_read_b128 v[188:191], v151 offset:2048
	ds_read_b128 v[192:195], v151 offset:3072
	global_load_lds_dwordx4 v136, s[24:25]
	s_add_i32 m0, s29, 0xe000
	ds_read_b128 v[206:209], v151 offset:4096
	ds_read_b128 v[210:213], v151 offset:5120
	ds_read_b128 v[214:217], v151 offset:6144
	ds_read_b128 v[218:221], v151 offset:7168
	global_load_lds_dwordx4 v138, s[24:25]
	s_waitcnt vmcnt(8)
	s_waitcnt lgkmcnt(0)
	s_barrier
	s_waitcnt lgkmcnt(0)
	v_mfma_f32_16x16x32_bf16 v[126:129], v[140:143], v[180:183], v[126:129]
	v_mfma_f32_16x16x32_bf16 v[126:129], v[152:155], v[184:187], v[126:129]
	v_mfma_f32_16x16x32_bf16 v[122:125], v[156:159], v[180:183], v[122:125]
	v_mfma_f32_16x16x32_bf16 v[122:125], v[160:163], v[184:187], v[122:125]
	v_mfma_f32_16x16x32_bf16 v[110:113], v[140:143], v[188:191], v[110:113]
	v_mfma_f32_16x16x32_bf16 v[110:113], v[152:155], v[192:195], v[110:113]
	v_mfma_f32_16x16x32_bf16 v[106:109], v[156:159], v[188:191], v[106:109]
	v_mfma_f32_16x16x32_bf16 v[106:109], v[160:163], v[192:195], v[106:109]
	v_mfma_f32_16x16x32_bf16 v[94:97], v[140:143], v[206:209], v[94:97]
	v_mfma_f32_16x16x32_bf16 v[94:97], v[152:155], v[210:213], v[94:97]
	v_mfma_f32_16x16x32_bf16 v[90:93], v[156:159], v[206:209], v[90:93]
	v_mfma_f32_16x16x32_bf16 v[90:93], v[160:163], v[210:213], v[90:93]
	v_mfma_f32_16x16x32_bf16 v[78:81], v[140:143], v[214:217], v[78:81]
	v_mfma_f32_16x16x32_bf16 v[78:81], v[152:155], v[218:221], v[78:81]
	v_mfma_f32_16x16x32_bf16 v[74:77], v[156:159], v[214:217], v[74:77]
	v_mfma_f32_16x16x32_bf16 v[74:77], v[160:163], v[218:221], v[74:77]
	v_mfma_f32_16x16x32_bf16 v[118:121], v[164:167], v[180:183], v[118:121]
	v_mfma_f32_16x16x32_bf16 v[118:121], v[168:171], v[184:187], v[118:121]
	v_mfma_f32_16x16x32_bf16 v[114:117], v[172:175], v[180:183], v[114:117]
	v_mfma_f32_16x16x32_bf16 v[114:117], v[176:179], v[184:187], v[114:117]
	v_mfma_f32_16x16x32_bf16 v[102:105], v[164:167], v[188:191], v[102:105]
	v_mfma_f32_16x16x32_bf16 v[102:105], v[168:171], v[192:195], v[102:105]
	v_mfma_f32_16x16x32_bf16 v[98:101], v[172:175], v[188:191], v[98:101]
	v_mfma_f32_16x16x32_bf16 v[98:101], v[176:179], v[192:195], v[98:101]
	v_mfma_f32_16x16x32_bf16 v[86:89], v[164:167], v[206:209], v[86:89]
	v_mfma_f32_16x16x32_bf16 v[86:89], v[168:171], v[210:213], v[86:89]
	v_mfma_f32_16x16x32_bf16 v[82:85], v[172:175], v[206:209], v[82:85]
	v_mfma_f32_16x16x32_bf16 v[82:85], v[176:179], v[210:213], v[82:85]
	v_mfma_f32_16x16x32_bf16 v[70:73], v[164:167], v[214:217], v[70:73]
	v_mfma_f32_16x16x32_bf16 v[70:73], v[168:171], v[218:221], v[70:73]
	v_mfma_f32_16x16x32_bf16 v[66:69], v[172:175], v[214:217], v[66:69]
	v_mfma_f32_16x16x32_bf16 v[66:69], v[176:179], v[218:221], v[66:69]
	s_barrier
	s_add_u32 s46, s22, 0x80000
	s_addc_u32 s47, s23, 0
	s_add_i32 s45, s45, s28
	s_mov_b32 m0, s45
	ds_read_b128 v[180:183], v151 offset:16384
	ds_read_b128 v[184:187], v151 offset:17408
	global_load_lds_dwordx4 v0, s[22:23]
	s_add_i32 m0, s45, 0x2000
	s_add_i32 s2, s2, s28
	ds_read_b128 v[188:191], v151 offset:18432
	ds_read_b128 v[192:195], v151 offset:19456
	global_load_lds_dwordx4 v130, s[22:23]
	s_mov_b32 m0, s2
	ds_read_b128 v[206:209], v151 offset:20480
	ds_read_b128 v[210:213], v151 offset:21504
	global_load_lds_dwordx4 v0, s[46:47]
	s_add_i32 m0, s2, 0x2000
	ds_read_b128 v[214:217], v151 offset:22528
	ds_read_b128 v[218:221], v151 offset:23552
	global_load_lds_dwordx4 v130, s[46:47]
	s_waitcnt vmcnt(6)
	s_waitcnt lgkmcnt(0)
	s_barrier
	s_waitcnt lgkmcnt(0)
	v_mfma_f32_16x16x32_bf16 v[62:65], v[140:143], v[180:183], v[62:65]
	v_mfma_f32_16x16x32_bf16 v[62:65], v[152:155], v[184:187], v[62:65]
	v_mfma_f32_16x16x32_bf16 v[58:61], v[156:159], v[180:183], v[58:61]
	v_mfma_f32_16x16x32_bf16 v[58:61], v[160:163], v[184:187], v[58:61]
	v_mfma_f32_16x16x32_bf16 v[46:49], v[140:143], v[188:191], v[46:49]
	v_mfma_f32_16x16x32_bf16 v[46:49], v[152:155], v[192:195], v[46:49]
	v_mfma_f32_16x16x32_bf16 v[42:45], v[156:159], v[188:191], v[42:45]
	v_mfma_f32_16x16x32_bf16 v[42:45], v[160:163], v[192:195], v[42:45]
	v_mfma_f32_16x16x32_bf16 v[30:33], v[140:143], v[206:209], v[30:33]
	v_mfma_f32_16x16x32_bf16 v[30:33], v[152:155], v[210:213], v[30:33]
	v_mfma_f32_16x16x32_bf16 v[26:29], v[156:159], v[206:209], v[26:29]
	v_mfma_f32_16x16x32_bf16 v[26:29], v[160:163], v[210:213], v[26:29]
	v_mfma_f32_16x16x32_bf16 v[14:17], v[140:143], v[214:217], v[14:17]
	v_mfma_f32_16x16x32_bf16 v[14:17], v[152:155], v[218:221], v[14:17]
	v_mfma_f32_16x16x32_bf16 v[10:13], v[156:159], v[214:217], v[10:13]
	v_mfma_f32_16x16x32_bf16 v[10:13], v[160:163], v[218:221], v[10:13]
	v_mfma_f32_16x16x32_bf16 v[54:57], v[164:167], v[180:183], v[54:57]
	v_mfma_f32_16x16x32_bf16 v[54:57], v[168:171], v[184:187], v[54:57]
	v_mfma_f32_16x16x32_bf16 v[50:53], v[172:175], v[180:183], v[50:53]
	v_mfma_f32_16x16x32_bf16 v[50:53], v[176:179], v[184:187], v[50:53]
	v_mfma_f32_16x16x32_bf16 v[38:41], v[164:167], v[188:191], v[38:41]
	v_mfma_f32_16x16x32_bf16 v[38:41], v[168:171], v[192:195], v[38:41]
	v_mfma_f32_16x16x32_bf16 v[34:37], v[172:175], v[188:191], v[34:37]
	v_mfma_f32_16x16x32_bf16 v[34:37], v[176:179], v[192:195], v[34:37]
	v_mfma_f32_16x16x32_bf16 v[22:25], v[164:167], v[206:209], v[22:25]
	v_mfma_f32_16x16x32_bf16 v[22:25], v[168:171], v[210:213], v[22:25]
	v_mfma_f32_16x16x32_bf16 v[18:21], v[172:175], v[206:209], v[18:21]
	v_mfma_f32_16x16x32_bf16 v[18:21], v[176:179], v[210:213], v[18:21]
	v_mfma_f32_16x16x32_bf16 v[6:9], v[164:167], v[214:217], v[6:9]
	v_mfma_f32_16x16x32_bf16 v[6:9], v[168:171], v[218:221], v[6:9]
	v_mfma_f32_16x16x32_bf16 v[2:5], v[172:175], v[214:217], v[2:5]
	v_mfma_f32_16x16x32_bf16 v[2:5], v[176:179], v[218:221], v[2:5]
	s_barrier
	s_add_u32 s26, s26, 0x80000
	s_addc_u32 s27, s27, 0
	s_add_u32 s100, s26, 0xfff80000
	s_addc_u32 s101, s27, -1
	s_add_i32 s2, 0, 0x18000
	s_add_i32 s45, 0, 0x1c000
	v_add_u32_e32 v160, s2, v148
	v_add_u32_e32 v176, s45, v148
	s_mov_b32 m0, s29
	ds_read_b128 v[140:143], v160
	ds_read_b128 v[152:155], v160 offset:1024
	ds_read_b128 v[156:159], v160 offset:2048
	ds_read_b128 v[160:163], v160 offset:3072
	global_load_lds_dwordx4 v134, s[100:101]
	s_mov_b32 m0, s30
	ds_read_b128 v[164:167], v176
	ds_read_b128 v[168:171], v176 offset:1024
	ds_read_b128 v[172:175], v176 offset:2048
	ds_read_b128 v[176:179], v176 offset:3072
	global_load_lds_dwordx4 v132, s[100:101]
	s_mov_b32 m0, s31
	ds_read_b128 v[180:183], v151 offset:32768
	ds_read_b128 v[184:187], v151 offset:33792
	ds_read_b128 v[188:191], v151 offset:34816
	ds_read_b128 v[192:195], v151 offset:35840
	global_load_lds_dwordx4 v134, s[26:27]
	s_mov_b32 m0, s33
	ds_read_b128 v[206:209], v151 offset:36864
	ds_read_b128 v[210:213], v151 offset:37888
	ds_read_b128 v[214:217], v151 offset:38912
	ds_read_b128 v[218:221], v151 offset:39936
	global_load_lds_dwordx4 v132, s[26:27]
	s_waitcnt vmcnt(8)
	s_waitcnt lgkmcnt(0)
	s_barrier
	s_waitcnt lgkmcnt(0)
	v_mfma_f32_16x16x32_bf16 v[126:129], v[140:143], v[180:183], v[126:129]
	v_mfma_f32_16x16x32_bf16 v[126:129], v[152:155], v[184:187], v[126:129]
	v_mfma_f32_16x16x32_bf16 v[122:125], v[156:159], v[180:183], v[122:125]
	v_mfma_f32_16x16x32_bf16 v[122:125], v[160:163], v[184:187], v[122:125]
	v_mfma_f32_16x16x32_bf16 v[110:113], v[140:143], v[188:191], v[110:113]
	v_mfma_f32_16x16x32_bf16 v[110:113], v[152:155], v[192:195], v[110:113]
	v_mfma_f32_16x16x32_bf16 v[106:109], v[156:159], v[188:191], v[106:109]
	v_mfma_f32_16x16x32_bf16 v[106:109], v[160:163], v[192:195], v[106:109]
	v_mfma_f32_16x16x32_bf16 v[94:97], v[140:143], v[206:209], v[94:97]
	v_mfma_f32_16x16x32_bf16 v[94:97], v[152:155], v[210:213], v[94:97]
	v_mfma_f32_16x16x32_bf16 v[90:93], v[156:159], v[206:209], v[90:93]
	v_mfma_f32_16x16x32_bf16 v[90:93], v[160:163], v[210:213], v[90:93]
	v_mfma_f32_16x16x32_bf16 v[78:81], v[140:143], v[214:217], v[78:81]
	v_mfma_f32_16x16x32_bf16 v[78:81], v[152:155], v[218:221], v[78:81]
	v_mfma_f32_16x16x32_bf16 v[74:77], v[156:159], v[214:217], v[74:77]
	v_mfma_f32_16x16x32_bf16 v[74:77], v[160:163], v[218:221], v[74:77]
	v_mfma_f32_16x16x32_bf16 v[118:121], v[164:167], v[180:183], v[118:121]
	v_mfma_f32_16x16x32_bf16 v[118:121], v[168:171], v[184:187], v[118:121]
	v_mfma_f32_16x16x32_bf16 v[114:117], v[172:175], v[180:183], v[114:117]
	v_mfma_f32_16x16x32_bf16 v[114:117], v[176:179], v[184:187], v[114:117]
	v_mfma_f32_16x16x32_bf16 v[102:105], v[164:167], v[188:191], v[102:105]
	v_mfma_f32_16x16x32_bf16 v[102:105], v[168:171], v[192:195], v[102:105]
	v_mfma_f32_16x16x32_bf16 v[98:101], v[172:175], v[188:191], v[98:101]
	v_mfma_f32_16x16x32_bf16 v[98:101], v[176:179], v[192:195], v[98:101]
	v_mfma_f32_16x16x32_bf16 v[86:89], v[164:167], v[206:209], v[86:89]
	v_mfma_f32_16x16x32_bf16 v[86:89], v[168:171], v[210:213], v[86:89]
	v_mfma_f32_16x16x32_bf16 v[82:85], v[172:175], v[206:209], v[82:85]
	v_mfma_f32_16x16x32_bf16 v[82:85], v[176:179], v[210:213], v[82:85]
	v_mfma_f32_16x16x32_bf16 v[70:73], v[164:167], v[214:217], v[70:73]
	v_mfma_f32_16x16x32_bf16 v[70:73], v[168:171], v[218:221], v[70:73]
	v_mfma_f32_16x16x32_bf16 v[66:69], v[172:175], v[214:217], v[66:69]
	v_mfma_f32_16x16x32_bf16 v[66:69], v[176:179], v[218:221], v[66:69]
	s_barrier
	s_add_u32 s22, s22, 0x80080
	s_addc_u32 s23, s23, 0
	s_add_u32 s46, s46, 0xfff80080
	s_addc_u32 s47, s47, -1
	s_add_i32 s2, s2, s28
	s_mov_b32 m0, s2
	ds_read_b128 v[180:183], v151 offset:49152
	ds_read_b128 v[184:187], v151 offset:50176
	global_load_lds_dwordx4 v0, s[46:47]
	s_add_i32 m0, s2, 0x2000
	s_add_i32 s2, s45, s28
	ds_read_b128 v[188:191], v151 offset:51200
	ds_read_b128 v[192:195], v151 offset:52224
	global_load_lds_dwordx4 v130, s[46:47]
	s_mov_b32 m0, s2
	ds_read_b128 v[206:209], v151 offset:53248
	ds_read_b128 v[210:213], v151 offset:54272
	global_load_lds_dwordx4 v0, s[22:23]
	s_add_i32 m0, s2, 0x2000
	ds_read_b128 v[214:217], v151 offset:55296
	ds_read_b128 v[218:221], v151 offset:56320
	global_load_lds_dwordx4 v130, s[22:23]
	s_waitcnt vmcnt(6)
	s_waitcnt lgkmcnt(0)
	s_barrier
	s_waitcnt lgkmcnt(0)
	v_mfma_f32_16x16x32_bf16 v[62:65], v[140:143], v[180:183], v[62:65]
	v_mfma_f32_16x16x32_bf16 v[62:65], v[152:155], v[184:187], v[62:65]
	v_mfma_f32_16x16x32_bf16 v[58:61], v[156:159], v[180:183], v[58:61]
	v_mfma_f32_16x16x32_bf16 v[58:61], v[160:163], v[184:187], v[58:61]
	v_mfma_f32_16x16x32_bf16 v[46:49], v[140:143], v[188:191], v[46:49]
	v_mfma_f32_16x16x32_bf16 v[46:49], v[152:155], v[192:195], v[46:49]
	v_mfma_f32_16x16x32_bf16 v[42:45], v[156:159], v[188:191], v[42:45]
	v_mfma_f32_16x16x32_bf16 v[42:45], v[160:163], v[192:195], v[42:45]
	v_mfma_f32_16x16x32_bf16 v[30:33], v[140:143], v[206:209], v[30:33]
	v_mfma_f32_16x16x32_bf16 v[30:33], v[152:155], v[210:213], v[30:33]
	v_mfma_f32_16x16x32_bf16 v[26:29], v[156:159], v[206:209], v[26:29]
	v_mfma_f32_16x16x32_bf16 v[26:29], v[160:163], v[210:213], v[26:29]
	v_mfma_f32_16x16x32_bf16 v[14:17], v[140:143], v[214:217], v[14:17]
	v_mfma_f32_16x16x32_bf16 v[14:17], v[152:155], v[218:221], v[14:17]
	v_mfma_f32_16x16x32_bf16 v[10:13], v[156:159], v[214:217], v[10:13]
	v_mfma_f32_16x16x32_bf16 v[10:13], v[160:163], v[218:221], v[10:13]
	v_mfma_f32_16x16x32_bf16 v[54:57], v[164:167], v[180:183], v[54:57]
	v_mfma_f32_16x16x32_bf16 v[54:57], v[168:171], v[184:187], v[54:57]
	v_mfma_f32_16x16x32_bf16 v[50:53], v[172:175], v[180:183], v[50:53]
	v_mfma_f32_16x16x32_bf16 v[50:53], v[176:179], v[184:187], v[50:53]
	v_mfma_f32_16x16x32_bf16 v[38:41], v[164:167], v[188:191], v[38:41]
	v_mfma_f32_16x16x32_bf16 v[38:41], v[168:171], v[192:195], v[38:41]
	v_mfma_f32_16x16x32_bf16 v[34:37], v[172:175], v[188:191], v[34:37]
	v_mfma_f32_16x16x32_bf16 v[34:37], v[176:179], v[192:195], v[34:37]
	v_mfma_f32_16x16x32_bf16 v[22:25], v[164:167], v[206:209], v[22:25]
	v_mfma_f32_16x16x32_bf16 v[22:25], v[168:171], v[210:213], v[22:25]
	v_mfma_f32_16x16x32_bf16 v[18:21], v[172:175], v[206:209], v[18:21]
	v_mfma_f32_16x16x32_bf16 v[18:21], v[176:179], v[210:213], v[18:21]
	v_mfma_f32_16x16x32_bf16 v[6:9], v[164:167], v[214:217], v[6:9]
	v_mfma_f32_16x16x32_bf16 v[6:9], v[168:171], v[218:221], v[6:9]
	v_mfma_f32_16x16x32_bf16 v[2:5], v[172:175], v[214:217], v[2:5]
	v_mfma_f32_16x16x32_bf16 v[2:5], v[176:179], v[218:221], v[2:5]
	s_barrier
	s_add_i32 s44, s44, 2
	s_add_u32 s24, s24, 0x100
	s_addc_u32 s25, s25, 0
	s_add_u32 s42, s42, 0x100
	s_addc_u32 s43, s43, 0
	s_cmp_gt_u32 s44, 29
	s_cbranch_scc0 .LBB0_408
	s_and_b64 vcc, exec, s[12:13]
	s_cbranch_vccz .LBB0_411
	s_barrier

.LBB0_440:
	s_add_u32 s2, s18, 0xfff80080
	s_addc_u32 s10, s19, -1
	s_add_i32 s47, 0, 0x10000
	s_cmp_eq_u32 s46, 28
	s_cselect_b32 s29, s25, s10
	s_cselect_b32 s28, s34, s2
	s_cselect_b32 s11, s23, s45
	s_cselect_b32 s10, s43, s44
	s_add_u32 s100, s18, 0xfff80000
	s_addc_u32 s101, s19, -1
	s_add_i32 s2, 0, 0x14000
	v_add_u32_e32 v154, s47, v162
	v_add_u32_e32 v184, s2, v162
	s_mov_b32 m0, s38
	ds_read_b128 v[130:133], v154
	ds_read_b128 v[134:137], v154 offset:1024
	ds_read_b128 v[150:153], v154 offset:2048
	ds_read_b128 v[154:157], v154 offset:3072
	global_load_lds_dwordx4 v144, s[100:101]
	s_mov_b32 m0, s39
	ds_read_b128 v[158:161], v184
	ds_read_b128 v[176:179], v184 offset:1024
	ds_read_b128 v[180:183], v184 offset:2048
	ds_read_b128 v[184:187], v184 offset:3072
	global_load_lds_dwordx4 v148, s[100:101]
	s_add_i32 m0, s31, 0xc000
	ds_read_b128 v[188:191], v175
	ds_read_b128 v[192:195], v175 offset:1024
	ds_read_b128 v[206:209], v175 offset:2048
	ds_read_b128 v[210:213], v175 offset:3072
	global_load_lds_dwordx4 v144, s[18:19]
	s_add_i32 m0, s31, 0xe000
	ds_read_b128 v[214:217], v175 offset:4096
	ds_read_b128 v[218:221], v175 offset:5120
	ds_read_b128 v[222:225], v175 offset:6144
	ds_read_b128 v[226:229], v175 offset:7168
	global_load_lds_dwordx4 v148, s[18:19]
	s_waitcnt vmcnt(8)
	s_waitcnt lgkmcnt(0)
	s_barrier
	s_waitcnt lgkmcnt(0)
	v_mfma_f32_16x16x32_bf16 v[126:129], v[130:133], v[188:191], v[126:129]
	v_mfma_f32_16x16x32_bf16 v[126:129], v[134:137], v[192:195], v[126:129]
	v_mfma_f32_16x16x32_bf16 v[122:125], v[150:153], v[188:191], v[122:125]
	v_mfma_f32_16x16x32_bf16 v[122:125], v[154:157], v[192:195], v[122:125]
	v_mfma_f32_16x16x32_bf16 v[110:113], v[130:133], v[206:209], v[110:113]
	v_mfma_f32_16x16x32_bf16 v[110:113], v[134:137], v[210:213], v[110:113]
	v_mfma_f32_16x16x32_bf16 v[106:109], v[150:153], v[206:209], v[106:109]
	v_mfma_f32_16x16x32_bf16 v[106:109], v[154:157], v[210:213], v[106:109]
	v_mfma_f32_16x16x32_bf16 v[94:97], v[130:133], v[214:217], v[94:97]
	v_mfma_f32_16x16x32_bf16 v[94:97], v[134:137], v[218:221], v[94:97]
	v_mfma_f32_16x16x32_bf16 v[90:93], v[150:153], v[214:217], v[90:93]
	v_mfma_f32_16x16x32_bf16 v[90:93], v[154:157], v[218:221], v[90:93]
	v_mfma_f32_16x16x32_bf16 v[78:81], v[130:133], v[222:225], v[78:81]
	v_mfma_f32_16x16x32_bf16 v[78:81], v[134:137], v[226:229], v[78:81]
	v_mfma_f32_16x16x32_bf16 v[74:77], v[150:153], v[222:225], v[74:77]
	v_mfma_f32_16x16x32_bf16 v[74:77], v[154:157], v[226:229], v[74:77]
	v_mfma_f32_16x16x32_bf16 v[118:121], v[158:161], v[188:191], v[118:121]
	v_mfma_f32_16x16x32_bf16 v[118:121], v[176:179], v[192:195], v[118:121]
	v_mfma_f32_16x16x32_bf16 v[114:117], v[180:183], v[188:191], v[114:117]
	v_mfma_f32_16x16x32_bf16 v[114:117], v[184:187], v[192:195], v[114:117]
	v_mfma_f32_16x16x32_bf16 v[102:105], v[158:161], v[206:209], v[102:105]
	v_mfma_f32_16x16x32_bf16 v[102:105], v[176:179], v[210:213], v[102:105]
	v_mfma_f32_16x16x32_bf16 v[98:101], v[180:183], v[206:209], v[98:101]
	v_mfma_f32_16x16x32_bf16 v[98:101], v[184:187], v[210:213], v[98:101]
	v_mfma_f32_16x16x32_bf16 v[86:89], v[158:161], v[214:217], v[86:89]
	v_mfma_f32_16x16x32_bf16 v[86:89], v[176:179], v[218:221], v[86:89]
	v_mfma_f32_16x16x32_bf16 v[82:85], v[180:183], v[214:217], v[82:85]
	v_mfma_f32_16x16x32_bf16 v[82:85], v[184:187], v[218:221], v[82:85]
	v_mfma_f32_16x16x32_bf16 v[70:73], v[158:161], v[222:225], v[70:73]
	v_mfma_f32_16x16x32_bf16 v[70:73], v[176:179], v[226:229], v[70:73]
	v_mfma_f32_16x16x32_bf16 v[66:69], v[180:183], v[222:225], v[66:69]
	v_mfma_f32_16x16x32_bf16 v[66:69], v[184:187], v[226:229], v[66:69]
	s_barrier
	s_add_u32 s52, s10, 0x80000
	s_addc_u32 s53, s11, 0
	s_add_i32 s47, s47, s30
	s_mov_b32 m0, s47
	ds_read_b128 v[188:191], v175 offset:16384
	ds_read_b128 v[192:195], v175 offset:17408
	global_load_lds_dwordx4 v0, s[10:11]
	s_add_i32 m0, s47, 0x2000
	s_add_i32 s2, s2, s30
	ds_read_b128 v[206:209], v175 offset:18432
	ds_read_b128 v[210:213], v175 offset:19456
	global_load_lds_dwordx4 v138, s[10:11]
	s_mov_b32 m0, s2
	ds_read_b128 v[214:217], v175 offset:20480
	ds_read_b128 v[218:221], v175 offset:21504
	global_load_lds_dwordx4 v0, s[52:53]
	s_add_i32 m0, s2, 0x2000
	ds_read_b128 v[222:225], v175 offset:22528
	ds_read_b128 v[226:229], v175 offset:23552
	global_load_lds_dwordx4 v138, s[52:53]
	s_waitcnt vmcnt(6)
	s_waitcnt lgkmcnt(0)
	s_barrier
	s_waitcnt lgkmcnt(0)
	v_mfma_f32_16x16x32_bf16 v[62:65], v[130:133], v[188:191], v[62:65]
	v_mfma_f32_16x16x32_bf16 v[62:65], v[134:137], v[192:195], v[62:65]
	v_mfma_f32_16x16x32_bf16 v[58:61], v[150:153], v[188:191], v[58:61]
	v_mfma_f32_16x16x32_bf16 v[58:61], v[154:157], v[192:195], v[58:61]
	v_mfma_f32_16x16x32_bf16 v[46:49], v[130:133], v[206:209], v[46:49]
	v_mfma_f32_16x16x32_bf16 v[46:49], v[134:137], v[210:213], v[46:49]
	v_mfma_f32_16x16x32_bf16 v[42:45], v[150:153], v[206:209], v[42:45]
	v_mfma_f32_16x16x32_bf16 v[42:45], v[154:157], v[210:213], v[42:45]
	v_mfma_f32_16x16x32_bf16 v[30:33], v[130:133], v[214:217], v[30:33]
	v_mfma_f32_16x16x32_bf16 v[30:33], v[134:137], v[218:221], v[30:33]
	v_mfma_f32_16x16x32_bf16 v[26:29], v[150:153], v[214:217], v[26:29]
	v_mfma_f32_16x16x32_bf16 v[26:29], v[154:157], v[218:221], v[26:29]
	v_mfma_f32_16x16x32_bf16 v[14:17], v[130:133], v[222:225], v[14:17]
	v_mfma_f32_16x16x32_bf16 v[14:17], v[134:137], v[226:229], v[14:17]
	v_mfma_f32_16x16x32_bf16 v[10:13], v[150:153], v[222:225], v[10:13]
	v_mfma_f32_16x16x32_bf16 v[10:13], v[154:157], v[226:229], v[10:13]
	v_mfma_f32_16x16x32_bf16 v[54:57], v[158:161], v[188:191], v[54:57]
	v_mfma_f32_16x16x32_bf16 v[54:57], v[176:179], v[192:195], v[54:57]
	v_mfma_f32_16x16x32_bf16 v[50:53], v[180:183], v[188:191], v[50:53]
	v_mfma_f32_16x16x32_bf16 v[50:53], v[184:187], v[192:195], v[50:53]
	v_mfma_f32_16x16x32_bf16 v[38:41], v[158:161], v[206:209], v[38:41]
	v_mfma_f32_16x16x32_bf16 v[38:41], v[176:179], v[210:213], v[38:41]
	v_mfma_f32_16x16x32_bf16 v[34:37], v[180:183], v[206:209], v[34:37]
	v_mfma_f32_16x16x32_bf16 v[34:37], v[184:187], v[210:213], v[34:37]
	v_mfma_f32_16x16x32_bf16 v[22:25], v[158:161], v[214:217], v[22:25]
	v_mfma_f32_16x16x32_bf16 v[22:25], v[176:179], v[218:221], v[22:25]
	v_mfma_f32_16x16x32_bf16 v[18:21], v[180:183], v[214:217], v[18:21]
	v_mfma_f32_16x16x32_bf16 v[18:21], v[184:187], v[218:221], v[18:21]
	v_mfma_f32_16x16x32_bf16 v[6:9], v[158:161], v[222:225], v[6:9]
	v_mfma_f32_16x16x32_bf16 v[6:9], v[176:179], v[226:229], v[6:9]
	v_mfma_f32_16x16x32_bf16 v[2:5], v[180:183], v[222:225], v[2:5]
	v_mfma_f32_16x16x32_bf16 v[2:5], v[184:187], v[226:229], v[2:5]
	s_barrier
	s_add_u32 s28, s28, 0x80000
	s_addc_u32 s29, s29, 0
	s_add_u32 s100, s28, 0xfff80000
	s_addc_u32 s101, s29, -1
	s_add_i32 s2, 0, 0x18000
	s_add_i32 s47, 0, 0x1c000
	v_add_u32_e32 v154, s2, v162
	v_add_u32_e32 v184, s47, v162
	s_mov_b32 m0, s31
	ds_read_b128 v[130:133], v154
	ds_read_b128 v[134:137], v154 offset:1024
	ds_read_b128 v[150:153], v154 offset:2048
	ds_read_b128 v[154:157], v154 offset:3072
	global_load_lds_dwordx4 v142, s[100:101]
	s_mov_b32 m0, s35
	ds_read_b128 v[158:161], v184
	ds_read_b128 v[176:179], v184 offset:1024
	ds_read_b128 v[180:183], v184 offset:2048
	ds_read_b128 v[184:187], v184 offset:3072
	global_load_lds_dwordx4 v140, s[100:101]
	s_mov_b32 m0, s36
	ds_read_b128 v[188:191], v175 offset:32768
	ds_read_b128 v[192:195], v175 offset:33792
	ds_read_b128 v[206:209], v175 offset:34816
	ds_read_b128 v[210:213], v175 offset:35840
	global_load_lds_dwordx4 v142, s[28:29]
	s_mov_b32 m0, s37
	ds_read_b128 v[214:217], v175 offset:36864
	ds_read_b128 v[218:221], v175 offset:37888
	ds_read_b128 v[222:225], v175 offset:38912
	ds_read_b128 v[226:229], v175 offset:39936
	global_load_lds_dwordx4 v140, s[28:29]
	s_waitcnt vmcnt(8)
	s_waitcnt lgkmcnt(0)
	s_barrier
	s_waitcnt lgkmcnt(0)
	v_mfma_f32_16x16x32_bf16 v[126:129], v[130:133], v[188:191], v[126:129]
	v_mfma_f32_16x16x32_bf16 v[126:129], v[134:137], v[192:195], v[126:129]
	v_mfma_f32_16x16x32_bf16 v[122:125], v[150:153], v[188:191], v[122:125]
	v_mfma_f32_16x16x32_bf16 v[122:125], v[154:157], v[192:195], v[122:125]
	v_mfma_f32_16x16x32_bf16 v[110:113], v[130:133], v[206:209], v[110:113]
	v_mfma_f32_16x16x32_bf16 v[110:113], v[134:137], v[210:213], v[110:113]
	v_mfma_f32_16x16x32_bf16 v[106:109], v[150:153], v[206:209], v[106:109]
	v_mfma_f32_16x16x32_bf16 v[106:109], v[154:157], v[210:213], v[106:109]
	v_mfma_f32_16x16x32_bf16 v[94:97], v[130:133], v[214:217], v[94:97]
	v_mfma_f32_16x16x32_bf16 v[94:97], v[134:137], v[218:221], v[94:97]
	v_mfma_f32_16x16x32_bf16 v[90:93], v[150:153], v[214:217], v[90:93]
	v_mfma_f32_16x16x32_bf16 v[90:93], v[154:157], v[218:221], v[90:93]
	v_mfma_f32_16x16x32_bf16 v[78:81], v[130:133], v[222:225], v[78:81]
	v_mfma_f32_16x16x32_bf16 v[78:81], v[134:137], v[226:229], v[78:81]
	v_mfma_f32_16x16x32_bf16 v[74:77], v[150:153], v[222:225], v[74:77]
	v_mfma_f32_16x16x32_bf16 v[74:77], v[154:157], v[226:229], v[74:77]
	v_mfma_f32_16x16x32_bf16 v[118:121], v[158:161], v[188:191], v[118:121]
	v_mfma_f32_16x16x32_bf16 v[118:121], v[176:179], v[192:195], v[118:121]
	v_mfma_f32_16x16x32_bf16 v[114:117], v[180:183], v[188:191], v[114:117]
	v_mfma_f32_16x16x32_bf16 v[114:117], v[184:187], v[192:195], v[114:117]
	v_mfma_f32_16x16x32_bf16 v[102:105], v[158:161], v[206:209], v[102:105]
	v_mfma_f32_16x16x32_bf16 v[102:105], v[176:179], v[210:213], v[102:105]
	v_mfma_f32_16x16x32_bf16 v[98:101], v[180:183], v[206:209], v[98:101]
	v_mfma_f32_16x16x32_bf16 v[98:101], v[184:187], v[210:213], v[98:101]
	v_mfma_f32_16x16x32_bf16 v[86:89], v[158:161], v[214:217], v[86:89]
	v_mfma_f32_16x16x32_bf16 v[86:89], v[176:179], v[218:221], v[86:89]
	v_mfma_f32_16x16x32_bf16 v[82:85], v[180:183], v[214:217], v[82:85]
	v_mfma_f32_16x16x32_bf16 v[82:85], v[184:187], v[218:221], v[82:85]
	v_mfma_f32_16x16x32_bf16 v[70:73], v[158:161], v[222:225], v[70:73]
	v_mfma_f32_16x16x32_bf16 v[70:73], v[176:179], v[226:229], v[70:73]
	v_mfma_f32_16x16x32_bf16 v[66:69], v[180:183], v[222:225], v[66:69]
	v_mfma_f32_16x16x32_bf16 v[66:69], v[184:187], v[226:229], v[66:69]
	s_barrier
	s_add_u32 s10, s10, 0x80080
	s_addc_u32 s11, s11, 0
	s_add_u32 s52, s52, 0xfff80080
	s_addc_u32 s53, s53, -1
	s_add_i32 s2, s2, s30
	s_mov_b32 m0, s2
	ds_read_b128 v[188:191], v175 offset:49152
	ds_read_b128 v[192:195], v175 offset:50176
	global_load_lds_dwordx4 v0, s[52:53]
	s_add_i32 m0, s2, 0x2000
	s_add_i32 s2, s47, s30
	ds_read_b128 v[206:209], v175 offset:51200
	ds_read_b128 v[210:213], v175 offset:52224
	global_load_lds_dwordx4 v138, s[52:53]
	s_mov_b32 m0, s2
	ds_read_b128 v[214:217], v175 offset:53248
	ds_read_b128 v[218:221], v175 offset:54272
	global_load_lds_dwordx4 v0, s[10:11]
	s_add_i32 m0, s2, 0x2000
	ds_read_b128 v[222:225], v175 offset:55296
	ds_read_b128 v[226:229], v175 offset:56320
	global_load_lds_dwordx4 v138, s[10:11]
	s_waitcnt vmcnt(6)
	s_waitcnt lgkmcnt(0)
	s_barrier
	s_waitcnt lgkmcnt(0)
	v_mfma_f32_16x16x32_bf16 v[62:65], v[130:133], v[188:191], v[62:65]
	v_mfma_f32_16x16x32_bf16 v[62:65], v[134:137], v[192:195], v[62:65]
	v_mfma_f32_16x16x32_bf16 v[58:61], v[150:153], v[188:191], v[58:61]
	v_mfma_f32_16x16x32_bf16 v[58:61], v[154:157], v[192:195], v[58:61]
	v_mfma_f32_16x16x32_bf16 v[46:49], v[130:133], v[206:209], v[46:49]
	v_mfma_f32_16x16x32_bf16 v[46:49], v[134:137], v[210:213], v[46:49]
	v_mfma_f32_16x16x32_bf16 v[42:45], v[150:153], v[206:209], v[42:45]
	v_mfma_f32_16x16x32_bf16 v[42:45], v[154:157], v[210:213], v[42:45]
	v_mfma_f32_16x16x32_bf16 v[30:33], v[130:133], v[214:217], v[30:33]
	v_mfma_f32_16x16x32_bf16 v[30:33], v[134:137], v[218:221], v[30:33]
	v_mfma_f32_16x16x32_bf16 v[26:29], v[150:153], v[214:217], v[26:29]
	v_mfma_f32_16x16x32_bf16 v[26:29], v[154:157], v[218:221], v[26:29]
	v_mfma_f32_16x16x32_bf16 v[14:17], v[130:133], v[222:225], v[14:17]
	v_mfma_f32_16x16x32_bf16 v[14:17], v[134:137], v[226:229], v[14:17]
	v_mfma_f32_16x16x32_bf16 v[10:13], v[150:153], v[222:225], v[10:13]
	v_mfma_f32_16x16x32_bf16 v[10:13], v[154:157], v[226:229], v[10:13]
	v_mfma_f32_16x16x32_bf16 v[54:57], v[158:161], v[188:191], v[54:57]
	v_mfma_f32_16x16x32_bf16 v[54:57], v[176:179], v[192:195], v[54:57]
	v_mfma_f32_16x16x32_bf16 v[50:53], v[180:183], v[188:191], v[50:53]
	v_mfma_f32_16x16x32_bf16 v[50:53], v[184:187], v[192:195], v[50:53]
	v_mfma_f32_16x16x32_bf16 v[38:41], v[158:161], v[206:209], v[38:41]
	v_mfma_f32_16x16x32_bf16 v[38:41], v[176:179], v[210:213], v[38:41]
	v_mfma_f32_16x16x32_bf16 v[34:37], v[180:183], v[206:209], v[34:37]
	v_mfma_f32_16x16x32_bf16 v[34:37], v[184:187], v[210:213], v[34:37]
	v_mfma_f32_16x16x32_bf16 v[22:25], v[158:161], v[214:217], v[22:25]
	v_mfma_f32_16x16x32_bf16 v[22:25], v[176:179], v[218:221], v[22:25]
	v_mfma_f32_16x16x32_bf16 v[18:21], v[180:183], v[214:217], v[18:21]
	v_mfma_f32_16x16x32_bf16 v[18:21], v[184:187], v[218:221], v[18:21]
	v_mfma_f32_16x16x32_bf16 v[6:9], v[158:161], v[222:225], v[6:9]
	v_mfma_f32_16x16x32_bf16 v[6:9], v[176:179], v[226:229], v[6:9]
	v_mfma_f32_16x16x32_bf16 v[2:5], v[180:183], v[222:225], v[2:5]
	v_mfma_f32_16x16x32_bf16 v[2:5], v[184:187], v[226:229], v[2:5]
	s_barrier
	s_add_i32 s46, s46, 2
	s_add_u32 s18, s18, 0x100
	s_addc_u32 s19, s19, 0
	s_add_u32 s44, s44, 0x100
	s_addc_u32 s45, s45, 0
	s_cmp_gt_u32 s46, 29
	s_cbranch_scc0 .LBB0_440
	s_and_b64 vcc, exec, s[20:21]
	s_cbranch_vccz .LBB0_443
	s_barrier

.LBB0_1102:
	s_add_u32 s2, s22, 0xfff80080
	s_addc_u32 s20, s23, -1
	s_add_i32 s45, 0, 0x10000
	s_cmp_eq_u32 s44, 28
	s_cselect_b32 s25, s15, s20
	s_cselect_b32 s24, s40, s2
	s_cselect_b32 s21, s13, s43
	s_cselect_b32 s20, s41, s42
	s_add_u32 s100, s22, 0xfff80000
	s_addc_u32 s101, s23, -1
	s_add_i32 s2, 0, 0x14000
	v_add_u32_e32 v142, s45, v226
	v_add_u32_e32 v160, s2, v226
	s_mov_b32 m0, s38
	ds_read_b128 v[130:133], v142
	ds_read_b128 v[134:137], v142 offset:1024
	ds_read_b128 v[138:141], v142 offset:2048
	ds_read_b128 v[142:145], v142 offset:3072
	global_load_lds_dwordx4 v194, s[100:101]
	s_mov_b32 m0, s39
	ds_read_b128 v[148:151], v160
	ds_read_b128 v[152:155], v160 offset:1024
	ds_read_b128 v[156:159], v160 offset:2048
	ds_read_b128 v[160:163], v160 offset:3072
	global_load_lds_dwordx4 v206, s[100:101]
	s_add_i32 m0, s30, 0xc000
	ds_read_b128 v[164:167], v228
	ds_read_b128 v[168:171], v228 offset:1024
	ds_read_b128 v[172:175], v228 offset:2048
	ds_read_b128 v[176:179], v228 offset:3072
	global_load_lds_dwordx4 v194, s[22:23]
	s_add_i32 m0, s30, 0xe000
	ds_read_b128 v[180:183], v228 offset:4096
	ds_read_b128 v[184:187], v228 offset:5120
	ds_read_b128 v[208:211], v228 offset:6144
	ds_read_b128 v[212:215], v228 offset:7168
	global_load_lds_dwordx4 v206, s[22:23]
	s_waitcnt vmcnt(8)
	s_waitcnt lgkmcnt(0)
	s_barrier
	s_waitcnt lgkmcnt(0)
	v_mfma_f32_16x16x32_bf16 v[126:129], v[130:133], v[164:167], v[126:129]
	v_mfma_f32_16x16x32_bf16 v[126:129], v[134:137], v[168:171], v[126:129]
	v_mfma_f32_16x16x32_bf16 v[122:125], v[138:141], v[164:167], v[122:125]
	v_mfma_f32_16x16x32_bf16 v[122:125], v[142:145], v[168:171], v[122:125]
	v_mfma_f32_16x16x32_bf16 v[110:113], v[130:133], v[172:175], v[110:113]
	v_mfma_f32_16x16x32_bf16 v[110:113], v[134:137], v[176:179], v[110:113]
	v_mfma_f32_16x16x32_bf16 v[106:109], v[138:141], v[172:175], v[106:109]
	v_mfma_f32_16x16x32_bf16 v[106:109], v[142:145], v[176:179], v[106:109]
	v_mfma_f32_16x16x32_bf16 v[94:97], v[130:133], v[180:183], v[94:97]
	v_mfma_f32_16x16x32_bf16 v[94:97], v[134:137], v[184:187], v[94:97]
	v_mfma_f32_16x16x32_bf16 v[90:93], v[138:141], v[180:183], v[90:93]
	v_mfma_f32_16x16x32_bf16 v[90:93], v[142:145], v[184:187], v[90:93]
	v_mfma_f32_16x16x32_bf16 v[78:81], v[130:133], v[208:211], v[78:81]
	v_mfma_f32_16x16x32_bf16 v[78:81], v[134:137], v[212:215], v[78:81]
	v_mfma_f32_16x16x32_bf16 v[74:77], v[138:141], v[208:211], v[74:77]
	v_mfma_f32_16x16x32_bf16 v[74:77], v[142:145], v[212:215], v[74:77]
	v_mfma_f32_16x16x32_bf16 v[118:121], v[148:151], v[164:167], v[118:121]
	v_mfma_f32_16x16x32_bf16 v[118:121], v[152:155], v[168:171], v[118:121]
	v_mfma_f32_16x16x32_bf16 v[114:117], v[156:159], v[164:167], v[114:117]
	v_mfma_f32_16x16x32_bf16 v[114:117], v[160:163], v[168:171], v[114:117]
	v_mfma_f32_16x16x32_bf16 v[102:105], v[148:151], v[172:175], v[102:105]
	v_mfma_f32_16x16x32_bf16 v[102:105], v[152:155], v[176:179], v[102:105]
	v_mfma_f32_16x16x32_bf16 v[98:101], v[156:159], v[172:175], v[98:101]
	v_mfma_f32_16x16x32_bf16 v[98:101], v[160:163], v[176:179], v[98:101]
	v_mfma_f32_16x16x32_bf16 v[86:89], v[148:151], v[180:183], v[86:89]
	v_mfma_f32_16x16x32_bf16 v[86:89], v[152:155], v[184:187], v[86:89]
	v_mfma_f32_16x16x32_bf16 v[82:85], v[156:159], v[180:183], v[82:85]
	v_mfma_f32_16x16x32_bf16 v[82:85], v[160:163], v[184:187], v[82:85]
	v_mfma_f32_16x16x32_bf16 v[70:73], v[148:151], v[208:211], v[70:73]
	v_mfma_f32_16x16x32_bf16 v[70:73], v[152:155], v[212:215], v[70:73]
	v_mfma_f32_16x16x32_bf16 v[66:69], v[156:159], v[208:211], v[66:69]
	v_mfma_f32_16x16x32_bf16 v[66:69], v[160:163], v[212:215], v[66:69]
	s_barrier
	s_add_u32 s46, s20, 0x80000
	s_addc_u32 s47, s21, 0
	s_add_i32 s45, s45, s29
	s_mov_b32 m0, s45
	ds_read_b128 v[164:167], v228 offset:16384
	ds_read_b128 v[168:171], v228 offset:17408
	global_load_lds_dwordx4 v0, s[20:21]
	s_add_i32 m0, s45, 0x2000
	s_add_i32 s2, s2, s29
	ds_read_b128 v[172:175], v228 offset:18432
	ds_read_b128 v[176:179], v228 offset:19456
	global_load_lds_dwordx4 v188, s[20:21]
	s_mov_b32 m0, s2
	ds_read_b128 v[180:183], v228 offset:20480
	ds_read_b128 v[184:187], v228 offset:21504
	global_load_lds_dwordx4 v0, s[46:47]
	s_add_i32 m0, s2, 0x2000
	ds_read_b128 v[208:211], v228 offset:22528
	ds_read_b128 v[212:215], v228 offset:23552
	global_load_lds_dwordx4 v188, s[46:47]
	s_waitcnt vmcnt(6)
	s_waitcnt lgkmcnt(0)
	s_barrier
	s_waitcnt lgkmcnt(0)
	v_mfma_f32_16x16x32_bf16 v[62:65], v[130:133], v[164:167], v[62:65]
	v_mfma_f32_16x16x32_bf16 v[62:65], v[134:137], v[168:171], v[62:65]
	v_mfma_f32_16x16x32_bf16 v[58:61], v[138:141], v[164:167], v[58:61]
	v_mfma_f32_16x16x32_bf16 v[58:61], v[142:145], v[168:171], v[58:61]
	v_mfma_f32_16x16x32_bf16 v[46:49], v[130:133], v[172:175], v[46:49]
	v_mfma_f32_16x16x32_bf16 v[46:49], v[134:137], v[176:179], v[46:49]
	v_mfma_f32_16x16x32_bf16 v[42:45], v[138:141], v[172:175], v[42:45]
	v_mfma_f32_16x16x32_bf16 v[42:45], v[142:145], v[176:179], v[42:45]
	v_mfma_f32_16x16x32_bf16 v[30:33], v[130:133], v[180:183], v[30:33]
	v_mfma_f32_16x16x32_bf16 v[30:33], v[134:137], v[184:187], v[30:33]
	v_mfma_f32_16x16x32_bf16 v[26:29], v[138:141], v[180:183], v[26:29]
	v_mfma_f32_16x16x32_bf16 v[26:29], v[142:145], v[184:187], v[26:29]
	v_mfma_f32_16x16x32_bf16 v[14:17], v[130:133], v[208:211], v[14:17]
	v_mfma_f32_16x16x32_bf16 v[14:17], v[134:137], v[212:215], v[14:17]
	v_mfma_f32_16x16x32_bf16 v[10:13], v[138:141], v[208:211], v[10:13]
	v_mfma_f32_16x16x32_bf16 v[10:13], v[142:145], v[212:215], v[10:13]
	v_mfma_f32_16x16x32_bf16 v[54:57], v[148:151], v[164:167], v[54:57]
	v_mfma_f32_16x16x32_bf16 v[54:57], v[152:155], v[168:171], v[54:57]
	v_mfma_f32_16x16x32_bf16 v[50:53], v[156:159], v[164:167], v[50:53]
	v_mfma_f32_16x16x32_bf16 v[50:53], v[160:163], v[168:171], v[50:53]
	v_mfma_f32_16x16x32_bf16 v[38:41], v[148:151], v[172:175], v[38:41]
	v_mfma_f32_16x16x32_bf16 v[38:41], v[152:155], v[176:179], v[38:41]
	v_mfma_f32_16x16x32_bf16 v[34:37], v[156:159], v[172:175], v[34:37]
	v_mfma_f32_16x16x32_bf16 v[34:37], v[160:163], v[176:179], v[34:37]
	v_mfma_f32_16x16x32_bf16 v[22:25], v[148:151], v[180:183], v[22:25]
	v_mfma_f32_16x16x32_bf16 v[22:25], v[152:155], v[184:187], v[22:25]
	v_mfma_f32_16x16x32_bf16 v[18:21], v[156:159], v[180:183], v[18:21]
	v_mfma_f32_16x16x32_bf16 v[18:21], v[160:163], v[184:187], v[18:21]
	v_mfma_f32_16x16x32_bf16 v[6:9], v[148:151], v[208:211], v[6:9]
	v_mfma_f32_16x16x32_bf16 v[6:9], v[152:155], v[212:215], v[6:9]
	v_mfma_f32_16x16x32_bf16 v[2:5], v[156:159], v[208:211], v[2:5]
	v_mfma_f32_16x16x32_bf16 v[2:5], v[160:163], v[212:215], v[2:5]
	s_barrier
	s_add_u32 s24, s24, 0x80000
	s_addc_u32 s25, s25, 0
	s_add_u32 s100, s24, 0xfff80000
	s_addc_u32 s101, s25, -1
	s_add_i32 s2, 0, 0x18000
	s_add_i32 s45, 0, 0x1c000
	v_add_u32_e32 v142, s2, v226
	v_add_u32_e32 v160, s45, v226
	s_mov_b32 m0, s30
	ds_read_b128 v[130:133], v142
	ds_read_b128 v[134:137], v142 offset:1024
	ds_read_b128 v[138:141], v142 offset:2048
	ds_read_b128 v[142:145], v142 offset:3072
	global_load_lds_dwordx4 v192, s[100:101]
	s_mov_b32 m0, s31
	ds_read_b128 v[148:151], v160
	ds_read_b128 v[152:155], v160 offset:1024
	ds_read_b128 v[156:159], v160 offset:2048
	ds_read_b128 v[160:163], v160 offset:3072
	global_load_lds_dwordx4 v190, s[100:101]
	s_mov_b32 m0, s35
	ds_read_b128 v[164:167], v228 offset:32768
	ds_read_b128 v[168:171], v228 offset:33792
	ds_read_b128 v[172:175], v228 offset:34816
	ds_read_b128 v[176:179], v228 offset:35840
	global_load_lds_dwordx4 v192, s[24:25]
	s_mov_b32 m0, s36
	ds_read_b128 v[180:183], v228 offset:36864
	ds_read_b128 v[184:187], v228 offset:37888
	ds_read_b128 v[208:211], v228 offset:38912
	ds_read_b128 v[212:215], v228 offset:39936
	global_load_lds_dwordx4 v190, s[24:25]
	s_waitcnt vmcnt(8)
	s_waitcnt lgkmcnt(0)
	s_barrier
	s_waitcnt lgkmcnt(0)
	v_mfma_f32_16x16x32_bf16 v[126:129], v[130:133], v[164:167], v[126:129]
	v_mfma_f32_16x16x32_bf16 v[126:129], v[134:137], v[168:171], v[126:129]
	v_mfma_f32_16x16x32_bf16 v[122:125], v[138:141], v[164:167], v[122:125]
	v_mfma_f32_16x16x32_bf16 v[122:125], v[142:145], v[168:171], v[122:125]
	v_mfma_f32_16x16x32_bf16 v[110:113], v[130:133], v[172:175], v[110:113]
	v_mfma_f32_16x16x32_bf16 v[110:113], v[134:137], v[176:179], v[110:113]
	v_mfma_f32_16x16x32_bf16 v[106:109], v[138:141], v[172:175], v[106:109]
	v_mfma_f32_16x16x32_bf16 v[106:109], v[142:145], v[176:179], v[106:109]
	v_mfma_f32_16x16x32_bf16 v[94:97], v[130:133], v[180:183], v[94:97]
	v_mfma_f32_16x16x32_bf16 v[94:97], v[134:137], v[184:187], v[94:97]
	v_mfma_f32_16x16x32_bf16 v[90:93], v[138:141], v[180:183], v[90:93]
	v_mfma_f32_16x16x32_bf16 v[90:93], v[142:145], v[184:187], v[90:93]
	v_mfma_f32_16x16x32_bf16 v[78:81], v[130:133], v[208:211], v[78:81]
	v_mfma_f32_16x16x32_bf16 v[78:81], v[134:137], v[212:215], v[78:81]
	v_mfma_f32_16x16x32_bf16 v[74:77], v[138:141], v[208:211], v[74:77]
	v_mfma_f32_16x16x32_bf16 v[74:77], v[142:145], v[212:215], v[74:77]
	v_mfma_f32_16x16x32_bf16 v[118:121], v[148:151], v[164:167], v[118:121]
	v_mfma_f32_16x16x32_bf16 v[118:121], v[152:155], v[168:171], v[118:121]
	v_mfma_f32_16x16x32_bf16 v[114:117], v[156:159], v[164:167], v[114:117]
	v_mfma_f32_16x16x32_bf16 v[114:117], v[160:163], v[168:171], v[114:117]
	v_mfma_f32_16x16x32_bf16 v[102:105], v[148:151], v[172:175], v[102:105]
	v_mfma_f32_16x16x32_bf16 v[102:105], v[152:155], v[176:179], v[102:105]
	v_mfma_f32_16x16x32_bf16 v[98:101], v[156:159], v[172:175], v[98:101]
	v_mfma_f32_16x16x32_bf16 v[98:101], v[160:163], v[176:179], v[98:101]
	v_mfma_f32_16x16x32_bf16 v[86:89], v[148:151], v[180:183], v[86:89]
	v_mfma_f32_16x16x32_bf16 v[86:89], v[152:155], v[184:187], v[86:89]
	v_mfma_f32_16x16x32_bf16 v[82:85], v[156:159], v[180:183], v[82:85]
	v_mfma_f32_16x16x32_bf16 v[82:85], v[160:163], v[184:187], v[82:85]
	v_mfma_f32_16x16x32_bf16 v[70:73], v[148:151], v[208:211], v[70:73]
	v_mfma_f32_16x16x32_bf16 v[70:73], v[152:155], v[212:215], v[70:73]
	v_mfma_f32_16x16x32_bf16 v[66:69], v[156:159], v[208:211], v[66:69]
	v_mfma_f32_16x16x32_bf16 v[66:69], v[160:163], v[212:215], v[66:69]
	s_barrier
	s_add_u32 s20, s20, 0x80080
	s_addc_u32 s21, s21, 0
	s_add_u32 s46, s46, 0xfff80080
	s_addc_u32 s47, s47, -1
	s_add_i32 s2, s2, s29
	s_mov_b32 m0, s2
	ds_read_b128 v[164:167], v228 offset:49152
	ds_read_b128 v[168:171], v228 offset:50176
	global_load_lds_dwordx4 v0, s[46:47]
	s_add_i32 m0, s2, 0x2000
	s_add_i32 s2, s45, s29
	ds_read_b128 v[172:175], v228 offset:51200
	ds_read_b128 v[176:179], v228 offset:52224
	global_load_lds_dwordx4 v188, s[46:47]
	s_mov_b32 m0, s2
	ds_read_b128 v[180:183], v228 offset:53248
	ds_read_b128 v[184:187], v228 offset:54272
	global_load_lds_dwordx4 v0, s[20:21]
	s_add_i32 m0, s2, 0x2000
	ds_read_b128 v[208:211], v228 offset:55296
	ds_read_b128 v[212:215], v228 offset:56320
	global_load_lds_dwordx4 v188, s[20:21]
	s_waitcnt vmcnt(6)
	s_waitcnt lgkmcnt(0)
	s_barrier
	s_waitcnt lgkmcnt(0)
	v_mfma_f32_16x16x32_bf16 v[62:65], v[130:133], v[164:167], v[62:65]
	v_mfma_f32_16x16x32_bf16 v[62:65], v[134:137], v[168:171], v[62:65]
	v_mfma_f32_16x16x32_bf16 v[58:61], v[138:141], v[164:167], v[58:61]
	v_mfma_f32_16x16x32_bf16 v[58:61], v[142:145], v[168:171], v[58:61]
	v_mfma_f32_16x16x32_bf16 v[46:49], v[130:133], v[172:175], v[46:49]
	v_mfma_f32_16x16x32_bf16 v[46:49], v[134:137], v[176:179], v[46:49]
	v_mfma_f32_16x16x32_bf16 v[42:45], v[138:141], v[172:175], v[42:45]
	v_mfma_f32_16x16x32_bf16 v[42:45], v[142:145], v[176:179], v[42:45]
	v_mfma_f32_16x16x32_bf16 v[30:33], v[130:133], v[180:183], v[30:33]
	v_mfma_f32_16x16x32_bf16 v[30:33], v[134:137], v[184:187], v[30:33]
	v_mfma_f32_16x16x32_bf16 v[26:29], v[138:141], v[180:183], v[26:29]
	v_mfma_f32_16x16x32_bf16 v[26:29], v[142:145], v[184:187], v[26:29]
	v_mfma_f32_16x16x32_bf16 v[14:17], v[130:133], v[208:211], v[14:17]
	v_mfma_f32_16x16x32_bf16 v[14:17], v[134:137], v[212:215], v[14:17]
	v_mfma_f32_16x16x32_bf16 v[10:13], v[138:141], v[208:211], v[10:13]
	v_mfma_f32_16x16x32_bf16 v[10:13], v[142:145], v[212:215], v[10:13]
	v_mfma_f32_16x16x32_bf16 v[54:57], v[148:151], v[164:167], v[54:57]
	v_mfma_f32_16x16x32_bf16 v[54:57], v[152:155], v[168:171], v[54:57]
	v_mfma_f32_16x16x32_bf16 v[50:53], v[156:159], v[164:167], v[50:53]
	v_mfma_f32_16x16x32_bf16 v[50:53], v[160:163], v[168:171], v[50:53]
	v_mfma_f32_16x16x32_bf16 v[38:41], v[148:151], v[172:175], v[38:41]
	v_mfma_f32_16x16x32_bf16 v[38:41], v[152:155], v[176:179], v[38:41]
	v_mfma_f32_16x16x32_bf16 v[34:37], v[156:159], v[172:175], v[34:37]
	v_mfma_f32_16x16x32_bf16 v[34:37], v[160:163], v[176:179], v[34:37]
	v_mfma_f32_16x16x32_bf16 v[22:25], v[148:151], v[180:183], v[22:25]
	v_mfma_f32_16x16x32_bf16 v[22:25], v[152:155], v[184:187], v[22:25]
	v_mfma_f32_16x16x32_bf16 v[18:21], v[156:159], v[180:183], v[18:21]
	v_mfma_f32_16x16x32_bf16 v[18:21], v[160:163], v[184:187], v[18:21]
	v_mfma_f32_16x16x32_bf16 v[6:9], v[148:151], v[208:211], v[6:9]
	v_mfma_f32_16x16x32_bf16 v[6:9], v[152:155], v[212:215], v[6:9]
	v_mfma_f32_16x16x32_bf16 v[2:5], v[156:159], v[208:211], v[2:5]
	v_mfma_f32_16x16x32_bf16 v[2:5], v[160:163], v[212:215], v[2:5]
	s_barrier
	s_add_i32 s44, s44, 2
	s_add_u32 s22, s22, 0x100
	s_addc_u32 s23, s23, 0
	s_add_u32 s42, s42, 0x100
	s_addc_u32 s43, s43, 0
	s_cmp_gt_u32 s44, 29
	s_cbranch_scc0 .LBB0_1102
	v_lshl_or_b32 v210, s3, 8, v227
	v_lshl_add_u32 v224, s34, 8, v147
	v_ashrrev_i32_e32 v211, 31, v210
	v_lshlrev_b64 v[130:131], 1, v[210:211]
	v_ashrrev_i32_e32 v225, 31, v224
	v_lshl_add_u64 v[132:133], s[8:9], 0, v[130:131]
	v_lshlrev_b64 v[134:135], 12, v[224:225]
	v_lshl_add_u64 v[136:137], v[132:133], 0, v[134:135]
	global_load_dwordx4 v[240:243], v[136:137], off
	global_load_dwordx4 v[244:247], v[136:137], off offset:256
	v_or_b32_e32 v222, 16, v224
	v_or_b32_e32 v220, 32, v224
	v_or_b32_e32 v218, 48, v224
	v_add_u32_e32 v216, 0x80, v224
	v_add_u32_e32 v214, 0x90, v224
	v_add_u32_e32 v212, 0xa0, v224
	v_add_u32_e32 v208, 0xb0, v224
	v_ashrrev_i32_e32 v223, 31, v222
	v_ashrrev_i32_e32 v221, 31, v220
	v_ashrrev_i32_e32 v219, 31, v218
	v_ashrrev_i32_e32 v217, 31, v216
	v_ashrrev_i32_e32 v215, 31, v214
	v_ashrrev_i32_e32 v213, 31, v212
	v_ashrrev_i32_e32 v209, 31, v208
	v_lshlrev_b64 v[136:137], 12, v[222:223]
	v_lshlrev_b64 v[138:139], 12, v[220:221]
	v_lshlrev_b64 v[140:141], 12, v[218:219]
	v_lshlrev_b64 v[142:143], 12, v[216:217]
	v_lshlrev_b64 v[144:145], 12, v[214:215]
	v_lshlrev_b64 v[148:149], 12, v[212:213]
	v_lshlrev_b64 v[150:151], 12, v[208:209]
	v_lshl_add_u64 v[134:135], s[8:9], 0, v[134:135]
	v_lshl_add_u64 v[136:137], v[132:133], 0, v[136:137]
	v_lshl_add_u64 v[138:139], v[132:133], 0, v[138:139]
	v_lshl_add_u64 v[140:141], v[132:133], 0, v[140:141]
	v_lshl_add_u64 v[142:143], v[132:133], 0, v[142:143]
	v_lshl_add_u64 v[144:145], v[132:133], 0, v[144:145]
	v_lshl_add_u64 v[236:237], v[132:133], 0, v[148:149]
	v_lshl_add_u64 v[132:133], v[132:133], 0, v[150:151]
	v_lshl_add_u64 v[248:249], v[134:135], 0, v[130:131]
	global_load_dwordx4 v[184:187], v[136:137], off
	global_load_dwordx4 v[180:183], v[136:137], off offset:256
	global_load_dwordx4 v[176:179], v[138:139], off
	global_load_dwordx4 v[172:175], v[138:139], off offset:256
	global_load_dwordx4 v[168:171], v[140:141], off
	global_load_dwordx4 v[164:167], v[140:141], off offset:256
	global_load_dwordx4 v[160:163], v[142:143], off
	global_load_dwordx4 v[156:159], v[142:143], off offset:256
	global_load_dwordx4 v[152:155], v[144:145], off
	global_load_dwordx4 v[148:151], v[144:145], off offset:256
	s_nop 0
	global_load_dwordx4 v[142:145], v[236:237], off
	global_load_dwordx4 v[138:141], v[236:237], off offset:256
	global_load_dwordx4 v[134:137], v[132:133], off
	s_nop 0
	global_load_dwordx4 v[130:133], v[132:133], off offset:256
	s_lshl_b32 s20, s3, 2
	s_ashr_i32 s21, s20, 31
	s_waitcnt vmcnt(0)
	v_lshlrev_b32_e32 v236, 16, v240
	v_and_b32_e32 v237, 0xffff0000, v240
	v_lshlrev_b32_e32 v250, 16, v242
	v_and_b32_e32 v251, 0xffff0000, v242
	v_lshlrev_b32_e32 v242, 16, v243
	v_and_b32_e32 v243, 0xffff0000, v243
	v_lshlrev_b32_e32 v240, 16, v241
	v_and_b32_e32 v241, 0xffff0000, v241
	v_pk_add_f32 v[126:127], v[126:127], v[236:237]
	v_pk_add_f32 v[236:237], v[124:125], v[242:243]
	v_pk_add_f32 v[124:125], v[122:123], v[250:251]
	v_pk_add_f32 v[128:129], v[128:129], v[240:241]
	v_cvt_pk_bf16_f32 v122, v126, v127
	v_lshlrev_b32_e32 v252, 16, v244
	v_cvt_pk_bf16_f32 v123, v128, v129
	v_cvt_pk_bf16_f32 v124, v124, v125
	v_cvt_pk_bf16_f32 v125, v236, v237
	global_store_dwordx4 v[248:249], v[122:125], off
	v_lshlrev_b32_e32 v126, 16, v122
	v_lshlrev_b32_e32 v127, 16, v123
	v_and_b32_e32 v122, 0xffff0000, v122
	v_and_b32_e32 v123, 0xffff0000, v123
	v_lshlrev_b32_e32 v128, 16, v124
	v_and_b32_e32 v124, 0xffff0000, v124
	v_lshlrev_b32_e32 v129, 16, v125
	v_and_b32_e32 v125, 0xffff0000, v125
	v_mul_f32_e32 v122, v122, v122
	v_mul_f32_e32 v123, v123, v123
	v_mul_f32_e32 v124, v124, v124
	v_mul_f32_e32 v125, v125, v125
	v_fmac_f32_e32 v122, v126, v126
	v_fmac_f32_e32 v123, v127, v127
	v_fmac_f32_e32 v124, v128, v128
	v_fmac_f32_e32 v125, v129, v129
	v_add_f32_e32 v122, v122, v123
	v_add_f32_e32 v123, v124, v125
	v_and_b32_e32 v253, 0xffff0000, v244
	v_add_f32_e32 v128, v122, v123
	v_lshlrev_b32_e32 v122, 16, v245
	v_and_b32_e32 v123, 0xffff0000, v245
	v_lshlrev_b32_e32 v124, 16, v246
	v_and_b32_e32 v125, 0xffff0000, v246
	v_lshlrev_b32_e32 v126, 16, v247
	v_and_b32_e32 v127, 0xffff0000, v247
	v_pk_add_f32 v[120:121], v[120:121], v[122:123]
	v_pk_add_f32 v[118:119], v[118:119], v[252:253]
	v_pk_add_f32 v[122:123], v[116:117], v[126:127]
	v_pk_add_f32 v[116:117], v[114:115], v[124:125]
	v_cvt_pk_bf16_f32 v114, v118, v119
	v_cvt_pk_bf16_f32 v115, v120, v121
	s_nop 0
	v_cvt_pk_bf16_f32 v116, v116, v117
	v_cvt_pk_bf16_f32 v117, v122, v123
	global_store_dwordx4 v[248:249], v[114:117], off offset:256
	v_lshlrev_b32_e32 v118, 16, v114
	v_lshlrev_b32_e32 v119, 16, v115
	v_and_b32_e32 v114, 0xffff0000, v114
	v_and_b32_e32 v115, 0xffff0000, v115
	v_mul_f32_e32 v114, v114, v114
	v_mul_f32_e32 v115, v115, v115
	v_lshlrev_b32_e32 v120, 16, v116
	v_and_b32_e32 v116, 0xffff0000, v116
	v_lshlrev_b32_e32 v121, 16, v117
	v_and_b32_e32 v117, 0xffff0000, v117
	v_fmac_f32_e32 v114, v118, v118
	v_fmac_f32_e32 v115, v119, v119
	v_add_f32_e32 v114, v114, v115
	v_mul_f32_e32 v115, v116, v116
	v_mul_f32_e32 v116, v117, v117
	v_fmac_f32_e32 v115, v120, v120
	v_fmac_f32_e32 v116, v121, v121
	v_add_f32_e32 v115, v115, v116
	v_add_f32_e32 v114, v114, v115
	s_mov_b32 s2, 0
	v_add_f32_e32 v114, v128, v114
	v_mbcnt_lo_u32_b32 v115, -1, s2
	v_mbcnt_hi_u32_b32 v115, -1, v115
	v_lshlrev_b32_e32 v115, 2, v115
	v_xor_b32_e32 v115, 64, v115
	ds_bpermute_b32 v115, v115, v114
	s_mov_b32 s2, 0
	s_waitcnt lgkmcnt(0)
	v_add_f32_e32 v114, v114, v115
	v_mbcnt_lo_u32_b32 v115, -1, s2
	v_mbcnt_hi_u32_b32 v115, -1, v115
	v_lshlrev_b32_e32 v115, 2, v115
	v_xor_b32_e32 v115, 0x80, v115
	ds_bpermute_b32 v115, v115, v114
	s_and_saveexec_b64 s[22:23], s[4:5]
	s_cbranch_execz .LBB0_1105
	v_lshlrev_b64 v[116:117], 7, v[224:225]
	v_lshl_add_u64 v[116:117], s[10:11], 0, v[116:117]
	v_lshl_add_u64 v[116:117], s[20:21], 2, v[116:117]
	s_lshl_b32 s50, s37, 2
	v_lshl_add_u64 v[116:117], v[116:117], 0, s[50:51]
	s_waitcnt lgkmcnt(0)
	v_add_f32_e32 v114, v114, v115
	global_store_dword v[116:117], v114, off
